# v24 + mLSTM phase C V-tile staging with 8 loads in flight
# speedup vs baseline: 1.0053x; 1.0002x over previous
.LBB0_1656:
	v_mov_b64_e32 v[116:117], s[0:1]
	flat_load_dwordx2 v[2:3], v[116:117] offset:128
	s_ashr_i32 s2, s80, 31
	s_lshr_b32 s2, s2, 26
	s_add_i32 s2, s80, s2
	s_ashr_i32 s36, s2, 6
	s_ashr_i32 s40, s2, 9
	s_lshl_b32 s33, s36, 12
	s_and_b32 s3, s2, 0xffffffc0
	s_ashr_i32 s41, s40, 31
	s_sub_i32 s33, s81, s33
	s_sub_i32 s3, s80, s3
	s_and_b32 s2, s36, 7
	s_lshl_b64 s[40:41], s[40:41], 12
	s_ashr_i32 s37, s33, 31
	s_add_u32 s66, s40, s33
	s_addc_u32 s67, s41, s37
	s_add_i32 s40, s80, s36
	s_ashr_i32 s41, s40, 31
	s_lshl_b64 s[40:41], s[40:41], 2
	v_readlane_b32 s33, v254, 53
	v_lshl_add_u64 v[0:1], s[66:67], 0, v[88:89]
	s_add_u32 s40, s33, s40
	v_readlane_b32 s33, v254, 55
	v_lshlrev_b64 v[0:1], 6, v[0:1]
	s_addc_u32 s41, s33, s41
	v_lshl_add_u64 v[0:1], s[56:57], 0, v[0:1]
	s_lshl_b32 s44, s2, 2
	v_lshl_add_u64 v[0:1], v[0:1], 0, s[44:45]
	global_load_dword v80, v161, s[40:41]
	global_load_dword v4, v[0:1], off
	s_lshl_b32 s62, s2, 8
	s_mov_b32 s63, s45
	s_movk_i32 s33, 0x6000
	s_ashr_i32 s37, s36, 31
	s_lshl_b64 s[36:37], s[36:37], 6
	v_mov_b32_e32 v75, s67
	v_or_b32_e32 v74, s66, v90
	v_add_u32_e32 v29, 0x4400, v93
	s_waitcnt vmcnt(0) lgkmcnt(0)
	v_lshl_add_u64 v[2:3], v[2:3], 0, s[44:45]
	flat_load_dword v5, v[2:3]
	s_nop 0
	global_load_dword v0, v[0:1], off offset:32
	s_nop 0
	flat_load_dword v1, v[2:3] offset:32
	s_lshl_b32 s44, s2, 7
	v_lshl_add_u64 v[72:73], v[96:97], 0, s[44:45]
	v_lshl_add_u64 v[120:121], v[100:101], 0, s[44:45]
	s_waitcnt vmcnt(0) lgkmcnt(0)
	v_add_f32_e32 v4, v4, v5
	v_add_f32_e32 v0, v0, v1
	v_min_f32_e32 v1, 0, v0
	v_mul_f32_e64 v0, |v0|, s94
	v_exp_f32_e32 v0, v0
	s_nop 0
	v_add_f32_e32 v0, 1.0, v0
	v_log_f32_e32 v0, v0
	s_nop 0
	v_fmac_f32_e32 v1, 0xbf317218, v0
	ds_bpermute_b32 v0, v107, v1
	s_waitcnt lgkmcnt(0)
	v_add_f32_e32 v0, v1, v0
	v_cndmask_b32_e64 v0, v0, v1, s[6:7]
	ds_bpermute_b32 v1, v154, v0
	s_waitcnt lgkmcnt(0)
	v_add_f32_e32 v1, v0, v1
	v_cndmask_b32_e64 v0, v1, v0, s[8:9]
	ds_bpermute_b32 v1, v155, v0
	s_waitcnt lgkmcnt(0)
	v_add_f32_e32 v1, v0, v1
	v_cndmask_b32_e64 v0, v1, v0, s[10:11]
	ds_bpermute_b32 v1, v156, v0
	s_waitcnt lgkmcnt(0)
	v_add_f32_e32 v1, v0, v1
	v_cndmask_b32_e64 v0, v1, v0, s[12:13]
	ds_bpermute_b32 v1, v157, v0
	s_waitcnt lgkmcnt(0)
	v_add_f32_e32 v1, v0, v1
	v_cndmask_b32_e64 v0, v1, v0, s[14:15]
	ds_bpermute_b32 v1, v158, v0
	s_waitcnt lgkmcnt(0)
	v_add_f32_e32 v1, v0, v1
	v_cndmask_b32_e64 v0, v1, v0, s[16:17]
	v_sub_f32_e32 v1, v4, v0
	ds_bpermute_b32 v2, v107, v1
	v_mul_f32_e32 v0, 0x3fb8aa3b, v0
	ds_write_b32 v91, v0 offset:17920
	s_waitcnt lgkmcnt(1)
	v_max_f32_e32 v2, v2, v2
	v_max_f32_e32 v2, v1, v2
	v_cndmask_b32_e64 v2, v2, v1, s[6:7]
	ds_bpermute_b32 v3, v154, v2
	v_mul_f32_e32 v1, 0x3fb8aa3b, v1
	s_waitcnt lgkmcnt(0)
	v_max_f32_e32 v3, v3, v3
	v_max_f32_e32 v3, v2, v3
	v_cndmask_b32_e64 v2, v3, v2, s[8:9]
	ds_bpermute_b32 v3, v155, v2
	s_waitcnt lgkmcnt(0)
	v_max_f32_e32 v3, v3, v3
	v_max_f32_e32 v3, v2, v3
	v_cndmask_b32_e64 v2, v3, v2, s[10:11]
	ds_bpermute_b32 v3, v156, v2
	s_waitcnt lgkmcnt(0)
	v_max_f32_e32 v3, v3, v3
	v_max_f32_e32 v3, v2, v3
	v_cndmask_b32_e64 v2, v3, v2, s[12:13]
	ds_bpermute_b32 v3, v157, v2
	s_waitcnt lgkmcnt(0)
	v_max_f32_e32 v3, v3, v3
	v_max_f32_e32 v3, v2, v3
	v_cndmask_b32_e64 v2, v3, v2, s[14:15]
	ds_bpermute_b32 v3, v158, v2
	v_max_f32_e32 v4, v2, v2
	s_waitcnt lgkmcnt(0)
	v_max_f32_e32 v3, v3, v3
	v_max_f32_e32 v3, v4, v3
	v_cndmask_b32_e64 v2, v3, v2, s[16:17]
	v_max_f32_e32 v2, v2, v2
	v_max_f32_e32 v3, v80, v80
	v_max_f32_e32 v2, v3, v2
	v_mul_f32_e32 v2, 0x3fb8aa3b, v2
	ds_write2st64_b32 v91, v1, v2 offset0:68 offset1:69
	v_lshl_add_u64 v[0:1], s[66:67], 0, v[94:95]
	v_lshlrev_b64 v[0:1], 11, v[0:1]
	v_lshl_add_u64 v[0:1], s[58:59], 0, v[0:1]
	v_lshl_add_u64 v[0:1], v[0:1], 0, s[62:63]
	v_lshl_add_u64 v[4:5], v[0:1], 0, v[160:161]
	global_load_dwordx4 v[212:215], v[4:5], off
	v_add_co_u32_e32 v216, vcc, 0x2000, v4
	s_nop 1
	v_addc_co_u32_e32 v217, vcc, 0, v5, vcc
	global_load_dwordx4 v[216:219], v[216:217], off
	v_add_co_u32_e32 v220, vcc, 0x4000, v4
	s_nop 1
	v_addc_co_u32_e32 v221, vcc, 0, v5, vcc
	global_load_dwordx4 v[220:223], v[220:221], off
	v_add_co_u32_e32 v224, vcc, 0x6000, v4
	s_nop 1
	v_addc_co_u32_e32 v225, vcc, 0, v5, vcc
	global_load_dwordx4 v[224:227], v[224:225], off
	v_add_co_u32_e32 v236, vcc, 0x8000, v4
	s_nop 1
	v_addc_co_u32_e32 v237, vcc, 0, v5, vcc
	global_load_dwordx4 v[236:239], v[236:237], off
	v_add_co_u32_e32 v240, vcc, 0xa000, v4
	s_nop 1
	v_addc_co_u32_e32 v241, vcc, 0, v5, vcc
	global_load_dwordx4 v[240:243], v[240:241], off
	v_add_co_u32_e32 v244, vcc, 0xc000, v4
	s_nop 1
	v_addc_co_u32_e32 v245, vcc, 0, v5, vcc
	global_load_dwordx4 v[244:247], v[244:245], off
	v_add_co_u32_e32 v248, vcc, 0xe000, v4
	s_nop 1
	v_addc_co_u32_e32 v249, vcc, 0, v5, vcc
	global_load_dwordx4 v[248:251], v[248:249], off
	s_waitcnt vmcnt(7)
	ds_write_b128 v172, v[212:215]
	v_add_co_u32_e32 v212, vcc, 0x10000, v4
	s_nop 1
	v_addc_co_u32_e32 v213, vcc, 0, v5, vcc
	global_load_dwordx4 v[212:215], v[212:213], off
	s_waitcnt vmcnt(7)
	ds_write_b128 v172, v[216:219] offset:1088
	v_add_co_u32_e32 v216, vcc, 0x12000, v4
	s_nop 1
	v_addc_co_u32_e32 v217, vcc, 0, v5, vcc
	global_load_dwordx4 v[216:219], v[216:217], off
	s_waitcnt vmcnt(7)
	ds_write_b128 v172, v[220:223] offset:2176
	v_add_co_u32_e32 v220, vcc, 0x14000, v4
	s_nop 1
	v_addc_co_u32_e32 v221, vcc, 0, v5, vcc
	global_load_dwordx4 v[220:223], v[220:221], off
	s_waitcnt vmcnt(7)
	ds_write_b128 v172, v[224:227] offset:3264
	v_add_co_u32_e32 v224, vcc, 0x16000, v4
	s_nop 1
	v_addc_co_u32_e32 v225, vcc, 0, v5, vcc
	global_load_dwordx4 v[224:227], v[224:225], off
	s_waitcnt vmcnt(7)
	ds_write_b128 v172, v[236:239] offset:4352
	v_add_co_u32_e32 v236, vcc, 0x18000, v4
	s_nop 1
	v_addc_co_u32_e32 v237, vcc, 0, v5, vcc
	global_load_dwordx4 v[236:239], v[236:237], off
	s_waitcnt vmcnt(7)
	ds_write_b128 v172, v[240:243] offset:5440
	v_add_co_u32_e32 v240, vcc, 0x1a000, v4
	s_nop 1
	v_addc_co_u32_e32 v241, vcc, 0, v5, vcc
	global_load_dwordx4 v[240:243], v[240:241], off
	s_waitcnt vmcnt(7)
	ds_write_b128 v172, v[244:247] offset:6528
	v_add_co_u32_e32 v244, vcc, 0x1c000, v4
	s_nop 1
	v_addc_co_u32_e32 v245, vcc, 0, v5, vcc
	global_load_dwordx4 v[244:247], v[244:245], off
	s_waitcnt vmcnt(7)
	ds_write_b128 v172, v[248:251] offset:7616
	v_add_co_u32_e32 v248, vcc, 0x1e000, v4
	s_nop 1
	v_addc_co_u32_e32 v249, vcc, 0, v5, vcc
	global_load_dwordx4 v[248:251], v[248:249], off
	s_ashr_i32 s33, s3, 31
	s_add_u32 s36, s36, s3
	s_addc_u32 s37, s37, s33
	s_lshl_b64 s[40:41], s[36:37], 8
	v_lshl_add_u64 v[132:133], v[98:99], 0, s[40:41]
	v_readlane_b32 s40, v254, 56
	v_readlane_b32 s41, v254, 57
	s_lshl_b64 s[36:37], s[36:37], 14
	v_lshl_add_u64 v[124:125], v[108:109], 0, s[36:37]
	v_readlane_b32 s3, v254, 45
	s_add_u32 s64, s3, s62
	v_readlane_b32 s3, v254, 47
	s_addc_u32 s65, s3, 0
	s_movk_i32 s3, 0x3000
	s_lshl_b32 s44, s2, 9
	s_add_i32 s80, s80, s46
	s_add_i32 s81, s81, s82
	s_cmpk_lt_i32 s80, 0x800
	s_waitcnt vmcnt(7)
	ds_write_b128 v172, v[212:215] offset:8704
	s_waitcnt vmcnt(6)
	ds_write_b128 v172, v[216:219] offset:9792
	s_waitcnt vmcnt(5)
	ds_write_b128 v172, v[220:223] offset:10880
	s_waitcnt vmcnt(4)
	ds_write_b128 v172, v[224:227] offset:11968
	s_waitcnt vmcnt(3)
	ds_write_b128 v172, v[236:239] offset:13056
	s_waitcnt vmcnt(2)
	ds_write_b128 v172, v[240:243] offset:14144
	s_waitcnt vmcnt(1)
	ds_write_b128 v172, v[244:247] offset:15232
	s_waitcnt vmcnt(0)
	ds_write_b128 v172, v[248:251] offset:16320
	v_lshlrev_b64 v[0:1], 10, v[74:75]
	s_waitcnt lgkmcnt(0)
	v_lshl_add_u64 v[8:9], v[72:73], 0, v[0:1]
	ds_read2_b32 v[118:119], v29 offset0:64 offset1:96
	global_load_dwordx4 v[20:23], v[8:9], off
	global_load_dwordx4 v[16:19], v[132:133], off offset:16
	global_load_dwordx4 v[24:27], v[132:133], off
	s_waitcnt lgkmcnt(0)
	v_fma_f32 v81, v80, s52, -v118
	s_waitcnt vmcnt(2)
	v_and_b32_e32 v0, 0xffff0000, v20
	v_lshlrev_b32_e32 v42, 16, v20
	s_waitcnt vmcnt(0)
	v_mul_f32_e32 v44, v25, v0
	v_lshlrev_b32_e32 v0, 16, v23
	v_mul_f32_e32 v28, v18, v0
	v_and_b32_e32 v0, 0xffff0000, v23
	v_mul_f32_e32 v18, v19, v0
	global_load_dwordx4 v[32:35], v[8:9], off offset:32
	global_load_dwordx4 v[0:3], v[132:133], off offset:80
	global_load_dwordx4 v[4:7], v[132:133], off offset:64
	v_lshlrev_b32_e32 v40, 16, v21
	v_and_b32_e32 v38, 0xffff0000, v21
	v_lshlrev_b32_e32 v36, 16, v22
	v_and_b32_e32 v30, 0xffff0000, v22
	s_waitcnt vmcnt(2)
	v_and_b32_e32 v11, 0xffff0000, v32
	v_lshlrev_b32_e32 v10, 16, v32
	s_waitcnt vmcnt(0)
	v_mul_f32_e32 v12, v5, v11
	v_pk_fma_f32 v[4:5], v[4:5], v[10:11], v[12:13] op_sel_hi:[1,1,0]
	v_and_b32_e32 v11, 0xffff0000, v33
	v_lshlrev_b32_e32 v10, 16, v33
	v_pk_fma_f32 v[4:5], v[6:7], v[10:11], v[4:5]
	v_mul_f32_e32 v6, v7, v11
	v_pk_add_f32 v[4:5], v[6:7], v[4:5] op_sel_hi:[0,1]
	v_and_b32_e32 v7, 0xffff0000, v34
	v_lshlrev_b32_e32 v6, 16, v34
	v_pk_fma_f32 v[4:5], v[0:1], v[6:7], v[4:5]
	v_mul_f32_e32 v0, v1, v7
	v_pk_add_f32 v[0:1], v[0:1], v[4:5] op_sel_hi:[0,1]
	v_and_b32_e32 v5, 0xffff0000, v35
	v_lshlrev_b32_e32 v4, 16, v35
	v_pk_fma_f32 v[0:1], v[2:3], v[4:5], v[0:1]
	v_mul_f32_e32 v2, v3, v5
	v_pk_add_f32 v[46:47], v[2:3], v[0:1] op_sel_hi:[0,1]
	global_load_dwordx4 v[64:67], v[8:9], off offset:64
	global_load_dwordx4 v[0:3], v[132:133], off offset:144
	global_load_dwordx4 v[4:7], v[132:133], off offset:128
	s_waitcnt vmcnt(2)
	v_and_b32_e32 v11, 0xffff0000, v64
	v_lshlrev_b32_e32 v10, 16, v64
	s_waitcnt vmcnt(0)
	v_mul_f32_e32 v12, v5, v11
	v_pk_fma_f32 v[4:5], v[4:5], v[10:11], v[12:13] op_sel_hi:[1,1,0]
	v_and_b32_e32 v11, 0xffff0000, v65
	v_lshlrev_b32_e32 v10, 16, v65
	v_pk_fma_f32 v[4:5], v[6:7], v[10:11], v[4:5]
	v_mul_f32_e32 v6, v7, v11
	v_pk_add_f32 v[4:5], v[6:7], v[4:5] op_sel_hi:[0,1]
	v_and_b32_e32 v7, 0xffff0000, v66
	v_lshlrev_b32_e32 v6, 16, v66
	v_pk_fma_f32 v[4:5], v[0:1], v[6:7], v[4:5]
	v_mul_f32_e32 v0, v1, v7
	v_pk_add_f32 v[0:1], v[0:1], v[4:5] op_sel_hi:[0,1]
	v_and_b32_e32 v5, 0xffff0000, v67
	v_lshlrev_b32_e32 v4, 16, v67
	v_pk_fma_f32 v[0:1], v[2:3], v[4:5], v[0:1]
	v_mul_f32_e32 v2, v3, v5
	v_pk_add_f32 v[76:77], v[2:3], v[0:1] op_sel_hi:[0,1]
	global_load_dwordx4 v[68:71], v[8:9], off offset:96
	global_load_dwordx4 v[0:3], v[132:133], off offset:208
	global_load_dwordx4 v[4:7], v[132:133], off offset:192
	s_waitcnt vmcnt(2)
	v_and_b32_e32 v9, 0xffff0000, v68
	v_lshlrev_b32_e32 v8, 16, v68
	s_waitcnt vmcnt(0)
	v_mul_f32_e32 v10, v5, v9
	v_pk_fma_f32 v[4:5], v[4:5], v[8:9], v[10:11] op_sel_hi:[1,1,0]
	v_and_b32_e32 v9, 0xffff0000, v69
	v_lshlrev_b32_e32 v8, 16, v69
	v_pk_fma_f32 v[4:5], v[6:7], v[8:9], v[4:5]
	v_mul_f32_e32 v6, v7, v9
	v_pk_add_f32 v[4:5], v[6:7], v[4:5] op_sel_hi:[0,1]
	v_and_b32_e32 v7, 0xffff0000, v70
	v_lshlrev_b32_e32 v6, 16, v70
	v_pk_fma_f32 v[4:5], v[0:1], v[6:7], v[4:5]
	v_mul_f32_e32 v0, v1, v7
	v_pk_add_f32 v[0:1], v[0:1], v[4:5] op_sel_hi:[0,1]
	v_and_b32_e32 v5, 0xffff0000, v71
	v_lshlrev_b32_e32 v4, 16, v71
	v_pk_fma_f32 v[0:1], v[2:3], v[4:5], v[0:1]
	v_mul_f32_e32 v2, v3, v5
	v_pk_add_f32 v[78:79], v[2:3], v[0:1] op_sel_hi:[0,1]
	v_mov_b32_e32 v1, s67
	v_or_b32_e32 v0, s66, v92
	v_lshlrev_b64 v[0:1], 10, v[0:1]
	v_lshl_add_u64 v[134:135], v[120:121], 0, v[0:1]
	global_load_dwordx4 v[0:3], v[134:135], off
	global_load_dwordx4 v[48:51], v[134:135], off offset:32
	s_waitcnt vmcnt(1)
	v_mfma_f32_32x32x16_bf16 v[0:15], v[0:3], v[20:23], 0
	s_waitcnt vmcnt(0)
	v_mfma_f32_32x32x16_bf16 v[0:15], v[48:51], v[32:35], v[0:15]
	global_load_dwordx4 v[48:51], v[134:135], off offset:64
	s_waitcnt vmcnt(0)
	v_mfma_f32_32x32x16_bf16 v[0:15], v[48:51], v[64:67], v[0:15]
	global_load_dwordx4 v[48:51], v[134:135], off offset:96
	ds_read_b128 v[60:63], v105 offset:17408
	ds_read_b128 v[52:55], v105 offset:17424
	s_waitcnt lgkmcnt(1)
	v_sub_f32_e32 v19, v60, v118
	v_exp_f32_e32 v19, v19
	s_waitcnt vmcnt(0)
	v_mfma_f32_32x32x16_bf16 v[0:15], v[48:51], v[68:71], v[0:15]
	v_cndmask_b32_e64 v19, v19, 0, s[18:19]
	ds_read_b128 v[56:59], v105 offset:17472
	ds_read_b128 v[48:51], v105 offset:17488
	v_sub_f32_e32 v60, v60, v119
	v_exp_f32_e32 v60, v60
	s_nop 6
	v_mul_f32_e32 v138, v0, v19
	v_fma_f32 v45, v0, v19, 0
	v_sub_f32_e32 v0, v61, v118
	v_exp_f32_e32 v0, v0
	v_mov_b32_e32 v25, v5
	v_cndmask_b32_e64 v0, 0, v0, s[20:21]
	v_mul_f32_e32 v139, v1, v0
	v_fmac_f32_e32 v45, v1, v0
	v_sub_f32_e32 v0, v62, v118
	v_exp_f32_e32 v0, v0
	s_waitcnt lgkmcnt(1)
	v_sub_f32_e32 v1, v59, v118
	v_exp_f32_e32 v1, v1
	v_cndmask_b32_e64 v0, v0, 0, s[22:23]
	v_mul_f32_e32 v140, v2, v0
	v_fmac_f32_e32 v45, v2, v0
	v_sub_f32_e32 v0, v63, v118
	v_exp_f32_e32 v0, v0
	s_nop 0
	v_cndmask_b32_e64 v0, v0, 0, s[24:25]
	v_mul_f32_e32 v141, v3, v0
	v_fmac_f32_e32 v45, v3, v0
	v_sub_f32_e32 v0, v52, v118
	v_exp_f32_e32 v0, v0
	s_nop 0
	v_cndmask_b32_e64 v0, v0, 0, s[26:27]
	v_mul_f32_e32 v142, v4, v0
	v_fmac_f32_e32 v45, v4, v0
	v_sub_f32_e32 v0, v53, v118
	v_exp_f32_e32 v0, v0
	s_nop 0
	v_cndmask_b32_e64 v43, v0, 0, s[28:29]
	v_sub_f32_e32 v0, v54, v118
	v_exp_f32_e32 v0, v0
	v_pk_fma_f32 v[4:5], v[24:25], v[42:43], v[44:45]
	v_pk_mul_f32 v[86:87], v[24:25], v[42:43]
	v_cndmask_b32_e64 v41, v0, 0, s[30:31]
	v_sub_f32_e32 v0, v55, v118
	v_exp_f32_e32 v0, v0
	v_exp_f32_e32 v86, v81
	v_cndmask_b32_e64 v39, v0, 0, s[34:35]
	v_sub_f32_e32 v0, v56, v118
	v_exp_f32_e32 v0, v0
	s_nop 0
	v_cndmask_b32_e64 v37, v0, 0, s[40:41]
	v_sub_f32_e32 v0, v57, v118
	v_exp_f32_e32 v0, v0
	v_readlane_b32 s40, v254, 58
	v_readlane_b32 s41, v254, 59
	s_nop 1
	v_cndmask_b32_e64 v31, 0, v0, s[40:41]
	v_sub_f32_e32 v0, v58, v118
	v_exp_f32_e32 v0, v0
	v_readlane_b32 s40, v254, 60
	v_readlane_b32 s41, v254, 61
	s_nop 1
	v_cndmask_b32_e64 v1, v1, 0, s[40:41]
	v_readlane_b32 s40, v254, 62
	v_readlane_b32 s41, v254, 63
	s_nop 1
	v_cndmask_b32_e64 v0, v0, 0, s[40:41]
	v_pk_mul_f32 v[114:115], v[10:11], v[0:1]
	s_waitcnt lgkmcnt(0)
	v_sub_f32_e32 v1, v49, v118
	v_exp_f32_e32 v1, v1
	v_sub_f32_e32 v0, v48, v118
	v_exp_f32_e32 v0, v0
	v_readlane_b32 s40, v254, 27
	v_readlane_b32 s41, v254, 28
	v_mov_b32_e32 v10, v26
	v_mov_b32_e32 v11, v6
	v_cndmask_b32_e64 v1, v1, 0, s[40:41]
	v_readlane_b32 s40, v255, 0
	v_readlane_b32 s41, v255, 1
	v_pk_mul_f32 v[24:25], v[10:11], v[40:41]
	v_pk_fma_f32 v[4:5], v[10:11], v[40:41], v[4:5]
	v_cndmask_b32_e64 v0, v0, 0, s[40:41]
	v_pk_mul_f32 v[122:123], v[12:13], v[0:1]
	v_sub_f32_e32 v1, v51, v118
	v_exp_f32_e32 v1, v1
	v_sub_f32_e32 v0, v50, v118
	v_exp_f32_e32 v0, v0
	v_readlane_b32 s40, v255, 2
	v_readlane_b32 s41, v255, 3
	v_mov_b32_e32 v10, v27
	v_mov_b32_e32 v11, v7
	v_cndmask_b32_e64 v1, v1, 0, s[40:41]
	v_readlane_b32 s40, v255, 6
	v_readlane_b32 s41, v255, 7
	v_pk_mul_f32 v[26:27], v[6:7], v[38:39]
	v_pk_fma_f32 v[4:5], v[10:11], v[38:39], v[4:5]
	v_cndmask_b32_e64 v0, v0, 0, s[40:41]
	v_pk_mul_f32 v[136:137], v[14:15], v[0:1]
	global_load_dwordx4 v[82:85], v[124:125], off offset:96
	global_load_dwordx4 v[110:113], v[124:125], off offset:64
	global_load_dwordx4 v[128:131], v[124:125], off offset:32
	global_load_dwordx4 v[0:3], v[124:125], off
	v_mov_b32_e32 v6, v16
	v_mov_b32_e32 v7, v8
	v_pk_mul_f32 v[38:39], v[6:7], v[36:37]
	v_pk_fma_f32 v[4:5], v[6:7], v[36:37], v[4:5]
	v_mov_b32_e32 v6, v17
	v_mov_b32_e32 v7, v9
	ds_read2_b32 v[126:127], v29 offset0:128 offset1:160
	v_pk_fma_f32 v[4:5], v[6:7], v[30:31], v[4:5]
	v_mov_b32_e32 v29, v114
	v_pk_add_f32 v[4:5], v[28:29], v[4:5]
	v_mov_b32_e32 v19, v115
	v_pk_add_f32 v[4:5], v[18:19], v[4:5]
	v_mov_b32_e32 v6, v161
	v_mov_b32_e32 v7, v122
	v_pk_add_f32 v[4:5], v[6:7], v[4:5]
	v_mov_b32_e32 v47, v123
	v_pk_add_f32 v[4:5], v[46:47], v[4:5]
	v_mov_b32_e32 v77, v136
	v_pk_add_f32 v[4:5], v[76:77], v[4:5]
	v_mov_b32_e32 v79, v137
	v_pk_add_f32 v[4:5], v[78:79], v[4:5]
	ds_bpermute_b32 v6, v159, v4
	ds_bpermute_b32 v7, v159, v5
	v_pk_mul_f32 v[16:17], v[8:9], v[30:31]
	ds_read_b64_tr_b16 v[40:41], v173
	ds_read_b64_tr_b16 v[42:43], v173 offset:1088
	ds_read_b64_tr_b16 v[44:45], v173 offset:4352
	ds_read_b64_tr_b16 v[46:47], v173 offset:5440
	s_waitcnt lgkmcnt(4)
	v_pk_add_f32 v[4:5], v[4:5], v[6:7]
	s_nop 0
	v_fmac_f32_e32 v5, v86, v4
	v_add_f32_e32 v4, v118, v126
	v_exp_f32_e64 v4, -v4
	s_nop 0
	v_max_f32_e64 v4, |v5|, v4
	v_div_scale_f32 v5, s[36:37], v4, v4, 1.0
	v_rcp_f32_e32 v6, v5
	s_nop 0
	v_fma_f32 v7, -v5, v6, 1.0
	v_fmac_f32_e32 v6, v7, v6
	v_div_scale_f32 v7, vcc, 1.0, v4, 1.0
	v_mul_f32_e32 v8, v7, v6
	v_fma_f32 v9, -v5, v8, v7
	v_fmac_f32_e32 v8, v9, v6
	v_fma_f32 v5, -v5, v8, v7
	v_div_fmas_f32 v5, v5, v6, v8
	v_div_fixup_f32 v118, v5, v4, 1.0
	s_waitcnt vmcnt(0)
	v_mfma_f32_32x32x16_bf16 v[0:15], v[0:3], v[20:23], 0
	v_mfma_f32_32x32x16_bf16 v[0:15], v[128:131], v[32:35], v[0:15]
	v_add_co_u32_e32 v128, vcc, s95, v124
	s_nop 1
	v_addc_co_u32_e32 v129, vcc, 0, v125, vcc
	v_mfma_f32_32x32x16_bf16 v[0:15], v[110:113], v[64:67], v[0:15]
	v_cvt_pk_bf16_f32 v110, v39, v17
	v_cvt_pk_bf16_f32 v111, v114, v115
	v_cvt_pk_bf16_f32 v112, v122, v123
	v_cvt_pk_bf16_f32 v113, v136, v137
	v_add_co_u32_e32 v122, vcc, s47, v124
	global_load_dwordx4 v[16:19], v[128:129], off offset:32
	v_mfma_f32_32x32x16_bf16 v[0:15], v[82:85], v[68:71], v[0:15]
	v_cvt_pk_bf16_f32 v82, v138, v139
	v_cvt_pk_bf16_f32 v83, v140, v141
	v_cvt_pk_bf16_f32 v84, v142, v87
	v_cvt_pk_bf16_f32 v85, v25, v27
	v_addc_co_u32_e32 v123, vcc, 0, v125, vcc
	v_add_co_u32_e32 v130, vcc, s3, v124
	s_nop 5
	v_pk_mul_f32 v[14:15], v[86:87], v[14:15] op_sel_hi:[0,1]
	v_pk_mul_f32 v[12:13], v[86:87], v[12:13] op_sel_hi:[0,1]
	v_pk_mul_f32 v[10:11], v[86:87], v[10:11] op_sel_hi:[0,1]
	v_pk_mul_f32 v[8:9], v[86:87], v[8:9] op_sel_hi:[0,1]
	v_pk_mul_f32 v[6:7], v[86:87], v[6:7] op_sel_hi:[0,1]
	v_pk_mul_f32 v[4:5], v[86:87], v[4:5] op_sel_hi:[0,1]
	v_pk_mul_f32 v[2:3], v[86:87], v[2:3] op_sel_hi:[0,1]
	v_pk_mul_f32 v[0:1], v[86:87], v[0:1] op_sel_hi:[0,1]
	v_addc_co_u32_e32 v131, vcc, 0, v125, vcc
	s_waitcnt lgkmcnt(2)
	v_mfma_f32_32x32x16_bf16 v[0:15], v[40:43], v[82:85], v[0:15]
	v_readlane_b32 s2, v255, 4
	v_readlane_b32 s3, v255, 5
	s_nop 1
	v_cndmask_b32_e64 v60, v60, 0, s[2:3]
	v_readlane_b32 s2, v254, 21
	v_readlane_b32 s3, v254, 22
	s_waitcnt lgkmcnt(0)
	v_mfma_f32_32x32x16_bf16 v[0:15], v[44:47], v[110:113], v[0:15]
	s_nop 11
	v_pk_mul_f32 v[0:1], v[0:1], v[118:119] op_sel_hi:[1,0]
	s_nop 0
	v_pk_mul_f32 v[114:115], v[0:1], v[0:1]
	v_cvt_pk_bf16_f32 v87, v0, v1
	v_pk_mul_f32 v[0:1], v[2:3], v[118:119] op_sel_hi:[1,0]
	s_nop 0
	v_pk_mul_f32 v[136:137], v[0:1], v[0:1]
	v_cvt_pk_bf16_f32 v126, v0, v1
	v_pk_mul_f32 v[0:1], v[4:5], v[118:119] op_sel_hi:[1,0]
	s_nop 0
	v_pk_mul_f32 v[138:139], v[0:1], v[0:1]
	v_cvt_pk_bf16_f32 v194, v0, v1
	v_pk_mul_f32 v[0:1], v[6:7], v[118:119] op_sel_hi:[1,0]
	s_nop 0
	v_pk_mul_f32 v[140:141], v[0:1], v[0:1]
	v_cvt_pk_bf16_f32 v195, v0, v1
	v_pk_mul_f32 v[0:1], v[8:9], v[118:119] op_sel_hi:[1,0]
	s_nop 0
	v_pk_mul_f32 v[142:143], v[0:1], v[0:1]
	v_cvt_pk_bf16_f32 v196, v0, v1
	v_pk_mul_f32 v[0:1], v[10:11], v[118:119] op_sel_hi:[1,0]
	s_nop 0
	v_pk_mul_f32 v[144:145], v[0:1], v[0:1]
	v_cvt_pk_bf16_f32 v197, v0, v1
	v_pk_mul_f32 v[0:1], v[12:13], v[118:119] op_sel_hi:[1,0]
	s_nop 0
	v_pk_mul_f32 v[146:147], v[0:1], v[0:1]
	v_cvt_pk_bf16_f32 v198, v0, v1
	v_pk_mul_f32 v[0:1], v[14:15], v[118:119] op_sel_hi:[1,0]
	s_nop 0
	v_pk_mul_f32 v[148:149], v[0:1], v[0:1]
	v_cvt_pk_bf16_f32 v199, v0, v1
	global_load_dwordx4 v[0:3], v[122:123], off offset:-4096
	s_waitcnt vmcnt(0)
	v_mfma_f32_32x32x16_bf16 v[0:15], v[0:3], v[20:23], 0
	v_mfma_f32_32x32x16_bf16 v[0:15], v[16:19], v[32:35], v[0:15]
	global_load_dwordx4 v[16:19], v[128:129], off offset:64
	s_waitcnt vmcnt(0)
	v_mfma_f32_32x32x16_bf16 v[0:15], v[16:19], v[64:67], v[0:15]
	global_load_dwordx4 v[16:19], v[128:129], off offset:96
	ds_read_b64_tr_b16 v[28:29], v173 offset:64
	ds_read_b64_tr_b16 v[30:31], v173 offset:1152
	ds_read_b64_tr_b16 v[36:37], v173 offset:4416
	ds_read_b64_tr_b16 v[38:39], v173 offset:5504
	s_waitcnt vmcnt(0)
	v_mfma_f32_32x32x16_bf16 v[0:15], v[16:19], v[68:71], v[0:15]
	global_load_dwordx4 v[16:19], v[122:123], off offset:32
	s_nop 10
	v_pk_mul_f32 v[14:15], v[86:87], v[14:15] op_sel_hi:[0,1]
	v_pk_mul_f32 v[12:13], v[86:87], v[12:13] op_sel_hi:[0,1]
	v_pk_mul_f32 v[10:11], v[86:87], v[10:11] op_sel_hi:[0,1]
	v_pk_mul_f32 v[8:9], v[86:87], v[8:9] op_sel_hi:[0,1]
	v_pk_mul_f32 v[6:7], v[86:87], v[6:7] op_sel_hi:[0,1]
	v_pk_mul_f32 v[4:5], v[86:87], v[4:5] op_sel_hi:[0,1]
	v_pk_mul_f32 v[2:3], v[86:87], v[2:3] op_sel_hi:[0,1]
	v_pk_mul_f32 v[0:1], v[86:87], v[0:1] op_sel_hi:[0,1]
	s_waitcnt lgkmcnt(2)
	s_nop 0
	v_mfma_f32_32x32x16_bf16 v[0:15], v[28:31], v[82:85], v[0:15]
	s_waitcnt lgkmcnt(0)
	v_mfma_f32_32x32x16_bf16 v[0:15], v[36:39], v[110:113], v[0:15]
	s_nop 11
	v_pk_mul_f32 v[0:1], v[118:119], v[0:1] op_sel_hi:[0,1]
	v_pk_mul_f32 v[150:151], v[0:1], v[0:1]
	v_cvt_pk_bf16_f32 v200, v0, v1
	v_pk_mul_f32 v[0:1], v[118:119], v[2:3] op_sel_hi:[0,1]
	v_pk_mul_f32 v[152:153], v[0:1], v[0:1]
	v_cvt_pk_bf16_f32 v201, v0, v1
	v_pk_mul_f32 v[0:1], v[118:119], v[4:5] op_sel_hi:[0,1]
	v_pk_mul_f32 v[162:163], v[0:1], v[0:1]
	v_cvt_pk_bf16_f32 v202, v0, v1
	v_pk_mul_f32 v[0:1], v[118:119], v[6:7] op_sel_hi:[0,1]
	v_pk_mul_f32 v[164:165], v[0:1], v[0:1]
	v_cvt_pk_bf16_f32 v203, v0, v1
	v_pk_mul_f32 v[0:1], v[118:119], v[8:9] op_sel_hi:[0,1]
	v_pk_mul_f32 v[168:169], v[0:1], v[0:1]
	v_cvt_pk_bf16_f32 v204, v0, v1
	v_pk_mul_f32 v[0:1], v[118:119], v[10:11] op_sel_hi:[0,1]
	v_pk_mul_f32 v[170:171], v[0:1], v[0:1]
	v_cvt_pk_bf16_f32 v205, v0, v1
	v_pk_mul_f32 v[0:1], v[118:119], v[12:13] op_sel_hi:[0,1]
	v_pk_mul_f32 v[174:175], v[0:1], v[0:1]
	v_cvt_pk_bf16_f32 v206, v0, v1
	v_pk_mul_f32 v[0:1], v[118:119], v[14:15] op_sel_hi:[0,1]
	v_pk_mul_f32 v[176:177], v[0:1], v[0:1]
	v_cvt_pk_bf16_f32 v207, v0, v1
	global_load_dwordx4 v[0:3], v[122:123], off
	s_waitcnt vmcnt(0)
	v_mfma_f32_32x32x16_bf16 v[0:15], v[0:3], v[20:23], 0
	v_mfma_f32_32x32x16_bf16 v[0:15], v[16:19], v[32:35], v[0:15]
	global_load_dwordx4 v[16:19], v[122:123], off offset:64
	s_waitcnt vmcnt(0)
	v_mfma_f32_32x32x16_bf16 v[0:15], v[16:19], v[64:67], v[0:15]
	global_load_dwordx4 v[16:19], v[122:123], off offset:96
	s_waitcnt vmcnt(0)
	v_mfma_f32_32x32x16_bf16 v[0:15], v[16:19], v[68:71], v[0:15]
	ds_read_b64_tr_b16 v[16:17], v173 offset:128
	ds_read_b64_tr_b16 v[18:19], v173 offset:1216
	ds_read_b64_tr_b16 v[24:25], v173 offset:4480
	ds_read_b64_tr_b16 v[26:27], v173 offset:5568
	s_nop 7
	v_pk_mul_f32 v[14:15], v[86:87], v[14:15] op_sel_hi:[0,1]
	v_pk_mul_f32 v[12:13], v[86:87], v[12:13] op_sel_hi:[0,1]
	v_pk_mul_f32 v[10:11], v[86:87], v[10:11] op_sel_hi:[0,1]
	v_pk_mul_f32 v[8:9], v[86:87], v[8:9] op_sel_hi:[0,1]
	v_pk_mul_f32 v[6:7], v[86:87], v[6:7] op_sel_hi:[0,1]
	v_pk_mul_f32 v[4:5], v[86:87], v[4:5] op_sel_hi:[0,1]
	v_pk_mul_f32 v[2:3], v[86:87], v[2:3] op_sel_hi:[0,1]
	v_pk_mul_f32 v[0:1], v[86:87], v[0:1] op_sel_hi:[0,1]
	s_waitcnt lgkmcnt(2)
	s_nop 0
	v_mfma_f32_32x32x16_bf16 v[0:15], v[16:19], v[82:85], v[0:15]
	s_waitcnt lgkmcnt(0)
	v_mfma_f32_32x32x16_bf16 v[0:15], v[24:27], v[110:113], v[0:15]
	s_nop 11
	v_pk_mul_f32 v[0:1], v[118:119], v[0:1] op_sel_hi:[0,1]
	v_pk_mul_f32 v[178:179], v[0:1], v[0:1]
	v_cvt_pk_bf16_f32 v208, v0, v1
	v_pk_mul_f32 v[0:1], v[118:119], v[2:3] op_sel_hi:[0,1]
	v_pk_mul_f32 v[180:181], v[0:1], v[0:1]
	v_cvt_pk_bf16_f32 v209, v0, v1
	v_pk_mul_f32 v[0:1], v[118:119], v[4:5] op_sel_hi:[0,1]
	v_pk_mul_f32 v[182:183], v[0:1], v[0:1]
	v_cvt_pk_bf16_f32 v210, v0, v1
	v_pk_mul_f32 v[0:1], v[118:119], v[6:7] op_sel_hi:[0,1]
	v_pk_mul_f32 v[184:185], v[0:1], v[0:1]
	v_cvt_pk_bf16_f32 v81, v0, v1
	v_pk_mul_f32 v[0:1], v[118:119], v[8:9] op_sel_hi:[0,1]
	v_pk_mul_f32 v[186:187], v[0:1], v[0:1]
	v_cvt_pk_bf16_f32 v79, v0, v1
	v_pk_mul_f32 v[0:1], v[118:119], v[10:11] op_sel_hi:[0,1]
	v_pk_mul_f32 v[188:189], v[0:1], v[0:1]
	v_cvt_pk_bf16_f32 v78, v0, v1
	v_pk_mul_f32 v[0:1], v[118:119], v[12:13] op_sel_hi:[0,1]
	v_pk_mul_f32 v[190:191], v[0:1], v[0:1]
	v_cvt_pk_bf16_f32 v77, v0, v1
	v_pk_mul_f32 v[0:1], v[118:119], v[14:15] op_sel_hi:[0,1]
	v_pk_mul_f32 v[192:193], v[0:1], v[0:1]
	v_cvt_pk_bf16_f32 v76, v0, v1
	global_load_dwordx4 v[0:3], v[130:131], off
	s_waitcnt vmcnt(0)
	v_mfma_f32_32x32x16_bf16 v[0:15], v[0:3], v[20:23], 0
	global_load_dwordx4 v[20:23], v[130:131], off offset:32
	s_waitcnt vmcnt(0)
	v_mfma_f32_32x32x16_bf16 v[0:15], v[20:23], v[32:35], v[0:15]
	global_load_dwordx4 v[20:23], v[130:131], off offset:64
	s_waitcnt vmcnt(0)
	v_mfma_f32_32x32x16_bf16 v[0:15], v[20:23], v[64:67], v[0:15]
	global_load_dwordx4 v[20:23], v[130:131], off offset:96
	s_waitcnt vmcnt(0)
	v_mfma_f32_32x32x16_bf16 v[0:15], v[20:23], v[68:71], v[0:15]
	ds_read_b64_tr_b16 v[20:21], v173 offset:192
	ds_read_b64_tr_b16 v[22:23], v173 offset:1280
	ds_read_b64_tr_b16 v[32:33], v173 offset:4544
	ds_read_b64_tr_b16 v[34:35], v173 offset:5632
	v_lshlrev_b32_e32 v70, 16, v87
	v_and_b32_e32 v71, 0xffff0000, v87
	s_nop 5
	v_pk_mul_f32 v[14:15], v[86:87], v[14:15] op_sel_hi:[0,1]
	v_pk_mul_f32 v[12:13], v[86:87], v[12:13] op_sel_hi:[0,1]
	v_pk_mul_f32 v[10:11], v[86:87], v[10:11] op_sel_hi:[0,1]
	v_pk_mul_f32 v[8:9], v[86:87], v[8:9] op_sel_hi:[0,1]
	v_pk_mul_f32 v[6:7], v[86:87], v[6:7] op_sel_hi:[0,1]
	v_pk_mul_f32 v[4:5], v[86:87], v[4:5] op_sel_hi:[0,1]
	v_pk_mul_f32 v[2:3], v[86:87], v[2:3] op_sel_hi:[0,1]
	v_pk_mul_f32 v[0:1], v[86:87], v[0:1] op_sel_hi:[0,1]
	s_waitcnt lgkmcnt(2)
	s_nop 0
	v_mfma_f32_32x32x16_bf16 v[0:15], v[20:23], v[82:85], v[0:15]
	s_waitcnt lgkmcnt(0)
	v_mfma_f32_32x32x16_bf16 v[0:15], v[32:35], v[110:113], v[0:15]
	v_lshlrev_b64 v[110:111], 1, v[102:103]
	v_lshlrev_b64 v[112:113], 2, v[102:103]
	s_nop 9
	v_pk_mul_f32 v[0:1], v[118:119], v[0:1] op_sel_hi:[0,1]
	v_pk_mul_f32 v[68:69], v[0:1], v[0:1]
	v_cvt_pk_bf16_f32 v67, v0, v1
	v_pk_mul_f32 v[0:1], v[118:119], v[2:3] op_sel_hi:[0,1]
	v_pk_mul_f32 v[2:3], v[0:1], v[0:1]
	v_cvt_pk_bf16_f32 v66, v0, v1
	v_pk_mul_f32 v[0:1], v[118:119], v[4:5] op_sel_hi:[0,1]
	v_pk_mul_f32 v[4:5], v[118:119], v[6:7] op_sel_hi:[0,1]
	v_cvt_pk_bf16_f32 v65, v0, v1
	v_mov_b32_e32 v7, v0
	v_mov_b32_e32 v0, v5
	v_mov_b32_e32 v6, v4
	v_pk_mul_f32 v[0:1], v[0:1], v[0:1]
	v_cvt_pk_bf16_f32 v64, v4, v5
	v_pk_fma_f32 v[6:7], v[6:7], v[6:7], v[0:1]
	v_pk_mul_f32 v[0:1], v[118:119], v[8:9] op_sel_hi:[0,1]
	v_pk_mul_f32 v[4:5], v[118:119], v[10:11] op_sel_hi:[0,1]
	v_cvt_pk_bf16_f32 v9, v0, v1
	v_mov_b32_e32 v11, v0
	v_mov_b32_e32 v0, v5
	v_mov_b32_e32 v10, v4
	v_pk_mul_f32 v[0:1], v[0:1], v[0:1]
	v_cvt_pk_bf16_f32 v8, v4, v5
	v_pk_mul_f32 v[4:5], v[118:119], v[12:13] op_sel_hi:[0,1]
	v_pk_mul_f32 v[12:13], v[118:119], v[14:15] op_sel_hi:[0,1]
	v_pk_fma_f32 v[10:11], v[10:11], v[10:11], v[0:1]
	v_cvt_pk_bf16_f32 v1, v4, v5
	v_mov_b32_e32 v15, v4
	v_mov_b32_e32 v4, v13
	v_mov_b32_e32 v14, v12
	v_pk_mul_f32 v[4:5], v[4:5], v[4:5]
	v_add_f32_e32 v0, v138, v139
	v_pk_fma_f32 v[4:5], v[14:15], v[14:15], v[4:5]
	v_add_f32_e32 v14, v136, v137
	v_add_f32_e32 v15, v114, v115
	v_add_f32_e32 v14, v15, v14
	v_add_f32_e32 v0, v0, v14
	v_add_f32_e32 v14, v140, v141
	v_add_f32_e32 v0, v14, v0
	v_add_f32_e32 v14, v142, v143
	v_add_f32_e32 v0, v14, v0
	v_add_f32_e32 v14, v144, v145
	v_add_f32_e32 v0, v14, v0
	v_add_f32_e32 v14, v146, v147
	v_add_f32_e32 v0, v14, v0
	v_add_f32_e32 v14, v148, v149
	v_add_f32_e32 v0, v14, v0
	v_add_f32_e32 v14, v150, v151
	v_add_f32_e32 v0, v0, v14
	v_add_f32_e32 v14, v152, v153
	v_add_f32_e32 v0, v14, v0
	v_add_f32_e32 v14, v162, v163
	v_add_f32_e32 v0, v14, v0
	v_add_f32_e32 v14, v164, v165
	v_add_f32_e32 v0, v14, v0
	v_add_f32_e32 v14, v168, v169
	v_add_f32_e32 v0, v14, v0
	v_add_f32_e32 v14, v170, v171
	v_add_f32_e32 v0, v14, v0
	v_add_f32_e32 v14, v174, v175
	v_add_f32_e32 v0, v14, v0
	v_add_f32_e32 v14, v176, v177
	v_add_f32_e32 v0, v14, v0
	v_add_f32_e32 v14, v178, v179
	v_add_f32_e32 v0, v0, v14
	v_add_f32_e32 v14, v180, v181
	v_add_f32_e32 v0, v14, v0
	v_add_f32_e32 v14, v182, v183
	v_add_f32_e32 v0, v14, v0
	v_add_f32_e32 v14, v184, v185
	v_add_f32_e32 v0, v14, v0
	v_add_f32_e32 v14, v186, v187
	v_add_f32_e32 v0, v14, v0
	v_add_f32_e32 v14, v188, v189
	v_add_f32_e32 v0, v14, v0
	v_add_f32_e32 v14, v190, v191
	v_add_f32_e32 v0, v14, v0
	v_add_f32_e32 v14, v192, v193
	v_add_f32_e32 v0, v14, v0
	v_add_f32_e32 v14, v68, v69
	v_add_f32_e32 v0, v0, v14
	v_add_f32_e32 v2, v2, v3
	v_add_f32_e32 v0, v2, v0
	v_add_f32_e32 v0, v7, v0
	v_add_f32_e32 v0, v6, v0
	v_add_f32_e32 v0, v11, v0
	v_add_f32_e32 v0, v10, v0
	v_add_f32_e32 v0, v5, v0
	v_add_f32_e32 v0, v4, v0
	ds_bpermute_b32 v2, v159, v0
	v_cvt_pk_bf16_f32 v10, v12, v13
	v_mov_b32_e32 v115, s67
	v_or_b32_e32 v114, s66, v104
	v_fma_f32 v118, v80, s52, -v119
	s_waitcnt lgkmcnt(0)
	v_add_f32_e32 v0, v0, v2
	v_fmamk_f32 v0, v0, 0x3c000000, v231
	v_cmp_gt_f32_e64 s[36:37], s92, v0
	v_mul_f32_e32 v2, 0x4f800000, v0
	v_exp_f32_e32 v118, v118
	v_cndmask_b32_e64 v0, v0, v2, s[36:37]
	v_sqrt_f32_e32 v2, v0
	s_nop 0
	v_add_u32_e32 v3, -1, v2
	v_fma_f32 v4, -v3, v2, v0
	v_cmp_ge_f32_e32 vcc, 0, v4
	v_add_u32_e32 v4, 1, v2
	s_nop 0
	v_cndmask_b32_e32 v3, v2, v3, vcc
	v_fma_f32 v2, -v4, v2, v0
	v_cmp_lt_f32_e32 vcc, 0, v2
	s_nop 1
	v_cndmask_b32_e32 v2, v3, v4, vcc
	v_mul_f32_e32 v3, 0x37800000, v2
	v_cndmask_b32_e64 v2, v2, v3, s[36:37]
	v_cmp_class_f32_e32 vcc, v0, v232
	s_nop 1
	v_cndmask_b32_e32 v0, v2, v0, vcc
	v_div_scale_f32 v2, s[36:37], v0, v0, 1.0
	v_rcp_f32_e32 v3, v2
	s_nop 0
	v_fma_f32 v4, -v2, v3, 1.0
	v_fmac_f32_e32 v3, v4, v3
	v_div_scale_f32 v4, vcc, 1.0, v0, 1.0
	v_mul_f32_e32 v5, v4, v3
	v_fma_f32 v6, -v2, v5, v4
	v_fmac_f32_e32 v5, v6, v3
	v_fma_f32 v2, -v2, v5, v4
	v_div_fmas_f32 v2, v2, v3, v5
	v_div_fixup_f32 v0, v2, v0, 1.0
	flat_load_dwordx2 v[2:3], v[116:117] offset:136
	v_lshlrev_b64 v[4:5], 11, v[74:75]
	v_lshl_add_u64 v[6:7], s[64:65], 0, v[4:5]
	v_lshl_add_u64 v[4:5], s[60:61], 0, v[4:5]
	v_lshl_add_u64 v[68:69], v[4:5], 0, s[62:63]
	v_lshl_add_u64 v[4:5], v[6:7], 0, v[110:111]
	global_load_dwordx2 v[6:7], v[4:5], off
	v_pk_mul_f32 v[70:71], v[0:1], v[70:71] op_sel_hi:[0,1]
	s_waitcnt vmcnt(0) lgkmcnt(0)
	v_lshl_add_u64 v[2:3], v[2:3], 0, s[44:45]
	v_lshl_add_u64 v[2:3], v[2:3], 0, v[112:113]
	global_load_dwordx4 v[12:15], v[2:3], off
	v_lshlrev_b32_e32 v11, 16, v6
	v_and_b32_e32 v6, 0xffff0000, v6
	v_mul_f32_e32 v6, 0xbfb8aa3b, v6
	v_exp_f32_e32 v6, v6
	v_mul_f32_e32 v11, 0xbfb8aa3b, v11
	v_exp_f32_e32 v11, v11
	v_add_f32_e32 v6, 1.0, v6
	v_rcp_f32_e32 v75, v6
	v_lshlrev_b32_e32 v6, 16, v7
	v_and_b32_e32 v7, 0xffff0000, v7
	v_mul_f32_e32 v6, 0xbfb8aa3b, v6
	v_mul_f32_e32 v7, 0xbfb8aa3b, v7
	v_exp_f32_e32 v6, v6
	v_exp_f32_e32 v7, v7
	v_add_f32_e32 v11, 1.0, v11
	v_rcp_f32_e32 v74, v11
	v_add_f32_e32 v6, 1.0, v6
	v_add_f32_e32 v7, 1.0, v7
	v_rcp_f32_e32 v6, v6
	v_rcp_f32_e32 v7, v7
	s_waitcnt vmcnt(0)
	v_pk_mul_f32 v[12:13], v[12:13], v[70:71]
	v_lshlrev_b32_e32 v70, 16, v126
	v_and_b32_e32 v71, 0xffff0000, v126
	v_pk_mul_f32 v[70:71], v[0:1], v[70:71] op_sel_hi:[0,1]
	v_pk_mul_f32 v[14:15], v[14:15], v[70:71]
	v_pk_mul_f32 v[12:13], v[74:75], v[12:13]
	v_pk_mul_f32 v[6:7], v[6:7], v[14:15]
	v_cvt_pk_bf16_f32 v12, v12, v13
	v_cvt_pk_bf16_f32 v13, v6, v7
	v_lshl_add_u64 v[6:7], v[68:69], 0, v[110:111]
	global_store_dwordx2 v[6:7], v[12:13], off
	global_load_dwordx4 v[12:15], v[2:3], off offset:32
	s_nop 0
	global_load_dwordx2 v[68:69], v[4:5], off offset:16
	v_lshlrev_b32_e32 v70, 16, v194
	v_and_b32_e32 v71, 0xffff0000, v194
	v_pk_mul_f32 v[70:71], v[0:1], v[70:71] op_sel_hi:[0,1]
	s_waitcnt vmcnt(1)
	v_pk_mul_f32 v[12:13], v[12:13], v[70:71]
	s_waitcnt vmcnt(0)
	v_lshlrev_b32_e32 v11, 16, v68
	v_mul_f32_e32 v11, 0xbfb8aa3b, v11
	v_exp_f32_e32 v11, v11
	v_lshlrev_b32_e32 v70, 16, v195
	v_and_b32_e32 v71, 0xffff0000, v195
	v_pk_mul_f32 v[70:71], v[0:1], v[70:71] op_sel_hi:[0,1]
	v_add_f32_e32 v11, 1.0, v11
	v_rcp_f32_e32 v74, v11
	v_and_b32_e32 v11, 0xffff0000, v68
	v_mul_f32_e32 v11, 0xbfb8aa3b, v11
	v_exp_f32_e32 v11, v11
	v_pk_mul_f32 v[14:15], v[14:15], v[70:71]
	v_lshlrev_b32_e32 v70, 16, v196
	v_and_b32_e32 v71, 0xffff0000, v196
	v_add_f32_e32 v11, 1.0, v11
	v_rcp_f32_e32 v75, v11
	v_lshlrev_b32_e32 v11, 16, v69
	v_mul_f32_e32 v11, 0xbfb8aa3b, v11
	v_exp_f32_e32 v11, v11
	v_pk_mul_f32 v[12:13], v[74:75], v[12:13]
	v_pk_mul_f32 v[70:71], v[0:1], v[70:71] op_sel_hi:[0,1]
	v_cvt_pk_bf16_f32 v12, v12, v13
	v_add_f32_e32 v11, 1.0, v11
	v_rcp_f32_e32 v68, v11
	v_and_b32_e32 v11, 0xffff0000, v69
	v_mul_f32_e32 v11, 0xbfb8aa3b, v11
	v_exp_f32_e32 v11, v11
	s_nop 0
	v_add_f32_e32 v11, 1.0, v11
	v_rcp_f32_e32 v69, v11
	s_nop 0
	v_pk_mul_f32 v[14:15], v[68:69], v[14:15]
	s_nop 0
	v_cvt_pk_bf16_f32 v13, v14, v15
	global_store_dwordx2 v[6:7], v[12:13], off offset:16
	global_load_dwordx4 v[12:15], v[2:3], off offset:64
	s_nop 0
	global_load_dwordx2 v[68:69], v[4:5], off offset:32
	s_waitcnt vmcnt(1)
	v_pk_mul_f32 v[12:13], v[12:13], v[70:71]
	s_waitcnt vmcnt(0)
	v_lshlrev_b32_e32 v11, 16, v68
	v_mul_f32_e32 v11, 0xbfb8aa3b, v11
	v_exp_f32_e32 v11, v11
	v_lshlrev_b32_e32 v70, 16, v197
	v_and_b32_e32 v71, 0xffff0000, v197
	v_pk_mul_f32 v[70:71], v[0:1], v[70:71] op_sel_hi:[0,1]
	v_add_f32_e32 v11, 1.0, v11
	v_rcp_f32_e32 v74, v11
	v_and_b32_e32 v11, 0xffff0000, v68
	v_mul_f32_e32 v11, 0xbfb8aa3b, v11
	v_exp_f32_e32 v11, v11
	v_pk_mul_f32 v[14:15], v[14:15], v[70:71]
	v_lshlrev_b32_e32 v70, 16, v198
	v_and_b32_e32 v71, 0xffff0000, v198
	v_add_f32_e32 v11, 1.0, v11
	v_rcp_f32_e32 v75, v11
	v_lshlrev_b32_e32 v11, 16, v69
	v_mul_f32_e32 v11, 0xbfb8aa3b, v11
	v_exp_f32_e32 v11, v11
	v_pk_mul_f32 v[12:13], v[74:75], v[12:13]
	v_pk_mul_f32 v[70:71], v[0:1], v[70:71] op_sel_hi:[0,1]
	v_cvt_pk_bf16_f32 v12, v12, v13
	v_add_f32_e32 v11, 1.0, v11
	v_rcp_f32_e32 v68, v11
	v_and_b32_e32 v11, 0xffff0000, v69
	v_mul_f32_e32 v11, 0xbfb8aa3b, v11
	v_exp_f32_e32 v11, v11
	s_nop 0
	v_add_f32_e32 v11, 1.0, v11
	v_rcp_f32_e32 v69, v11
	s_nop 0
	v_pk_mul_f32 v[14:15], v[68:69], v[14:15]
	s_nop 0
	v_cvt_pk_bf16_f32 v13, v14, v15
	global_store_dwordx2 v[6:7], v[12:13], off offset:32
	global_load_dwordx4 v[12:15], v[2:3], off offset:96
	s_nop 0
	global_load_dwordx2 v[68:69], v[4:5], off offset:48
	s_waitcnt vmcnt(1)
	v_pk_mul_f32 v[12:13], v[12:13], v[70:71]
	s_waitcnt vmcnt(0)
	v_lshlrev_b32_e32 v11, 16, v68
	v_mul_f32_e32 v11, 0xbfb8aa3b, v11
	v_exp_f32_e32 v11, v11
	v_lshlrev_b32_e32 v70, 16, v199
	v_and_b32_e32 v71, 0xffff0000, v199
	v_pk_mul_f32 v[70:71], v[0:1], v[70:71] op_sel_hi:[0,1]
	v_add_f32_e32 v11, 1.0, v11
	v_rcp_f32_e32 v74, v11
	v_and_b32_e32 v11, 0xffff0000, v68
	v_mul_f32_e32 v11, 0xbfb8aa3b, v11
	v_exp_f32_e32 v11, v11
	v_pk_mul_f32 v[14:15], v[14:15], v[70:71]
	v_lshlrev_b32_e32 v70, 16, v200
	v_and_b32_e32 v71, 0xffff0000, v200
	v_add_f32_e32 v11, 1.0, v11
	v_rcp_f32_e32 v75, v11
	v_lshlrev_b32_e32 v11, 16, v69
	v_mul_f32_e32 v11, 0xbfb8aa3b, v11
	v_exp_f32_e32 v11, v11
	v_pk_mul_f32 v[12:13], v[12:13], v[74:75]
	v_pk_mul_f32 v[70:71], v[0:1], v[70:71] op_sel_hi:[0,1]
	v_cvt_pk_bf16_f32 v12, v12, v13
	v_add_f32_e32 v11, 1.0, v11
	v_rcp_f32_e32 v68, v11
	v_and_b32_e32 v11, 0xffff0000, v69
	v_mul_f32_e32 v11, 0xbfb8aa3b, v11
	v_exp_f32_e32 v11, v11
	s_nop 0
	v_add_f32_e32 v11, 1.0, v11
	v_rcp_f32_e32 v69, v11
	s_nop 0
	v_pk_mul_f32 v[14:15], v[14:15], v[68:69]
	s_nop 0
	v_cvt_pk_bf16_f32 v13, v14, v15
	global_store_dwordx2 v[6:7], v[12:13], off offset:48
	global_load_dwordx4 v[12:15], v[2:3], off offset:128
	s_nop 0
	global_load_dwordx2 v[68:69], v[4:5], off offset:64
	s_waitcnt vmcnt(1)
	v_pk_mul_f32 v[12:13], v[12:13], v[70:71]
	s_waitcnt vmcnt(0)
	v_lshlrev_b32_e32 v11, 16, v68
	v_mul_f32_e32 v11, 0xbfb8aa3b, v11
	v_exp_f32_e32 v11, v11
	v_lshlrev_b32_e32 v70, 16, v201
	v_and_b32_e32 v71, 0xffff0000, v201
	v_pk_mul_f32 v[70:71], v[0:1], v[70:71] op_sel_hi:[0,1]
	v_add_f32_e32 v11, 1.0, v11
	v_rcp_f32_e32 v74, v11
	v_and_b32_e32 v11, 0xffff0000, v68
	v_mul_f32_e32 v11, 0xbfb8aa3b, v11
	v_exp_f32_e32 v11, v11
	v_pk_mul_f32 v[14:15], v[14:15], v[70:71]
	v_lshlrev_b32_e32 v70, 16, v202
	v_and_b32_e32 v71, 0xffff0000, v202
	v_add_f32_e32 v11, 1.0, v11
	v_rcp_f32_e32 v75, v11
	v_lshlrev_b32_e32 v11, 16, v69
	v_mul_f32_e32 v11, 0xbfb8aa3b, v11
	v_exp_f32_e32 v11, v11
	v_pk_mul_f32 v[12:13], v[12:13], v[74:75]
	v_pk_mul_f32 v[70:71], v[0:1], v[70:71] op_sel_hi:[0,1]
	v_cvt_pk_bf16_f32 v12, v12, v13
	v_add_f32_e32 v11, 1.0, v11
	v_rcp_f32_e32 v68, v11
	v_and_b32_e32 v11, 0xffff0000, v69
	v_mul_f32_e32 v11, 0xbfb8aa3b, v11
	v_exp_f32_e32 v11, v11
	s_nop 0
	v_add_f32_e32 v11, 1.0, v11
	v_rcp_f32_e32 v69, v11
	s_nop 0
	v_pk_mul_f32 v[14:15], v[14:15], v[68:69]
	s_nop 0
	v_cvt_pk_bf16_f32 v13, v14, v15
	global_store_dwordx2 v[6:7], v[12:13], off offset:64
	global_load_dwordx4 v[12:15], v[2:3], off offset:160
	s_nop 0
	global_load_dwordx2 v[68:69], v[4:5], off offset:80
	s_waitcnt vmcnt(1)
	v_pk_mul_f32 v[12:13], v[70:71], v[12:13]
	s_waitcnt vmcnt(0)
	v_lshlrev_b32_e32 v11, 16, v68
	v_mul_f32_e32 v11, 0xbfb8aa3b, v11
	v_exp_f32_e32 v11, v11
	v_lshlrev_b32_e32 v70, 16, v203
	v_and_b32_e32 v71, 0xffff0000, v203
	v_pk_mul_f32 v[70:71], v[0:1], v[70:71] op_sel_hi:[0,1]
	v_add_f32_e32 v11, 1.0, v11
	v_rcp_f32_e32 v74, v11
	v_and_b32_e32 v11, 0xffff0000, v68
	v_mul_f32_e32 v11, 0xbfb8aa3b, v11
	v_exp_f32_e32 v11, v11
	v_pk_mul_f32 v[14:15], v[70:71], v[14:15]
	v_lshlrev_b32_e32 v70, 16, v204
	v_and_b32_e32 v71, 0xffff0000, v204
	v_add_f32_e32 v11, 1.0, v11
	v_rcp_f32_e32 v75, v11
	v_lshlrev_b32_e32 v11, 16, v69
	v_mul_f32_e32 v11, 0xbfb8aa3b, v11
	v_exp_f32_e32 v11, v11
	v_pk_mul_f32 v[12:13], v[12:13], v[74:75]
	v_pk_mul_f32 v[70:71], v[0:1], v[70:71] op_sel_hi:[0,1]
	v_cvt_pk_bf16_f32 v12, v12, v13
	v_add_f32_e32 v11, 1.0, v11
	v_rcp_f32_e32 v68, v11
	v_and_b32_e32 v11, 0xffff0000, v69
	v_mul_f32_e32 v11, 0xbfb8aa3b, v11
	v_exp_f32_e32 v11, v11
	s_nop 0
	v_add_f32_e32 v11, 1.0, v11
	v_rcp_f32_e32 v69, v11
	s_nop 0
	v_pk_mul_f32 v[14:15], v[14:15], v[68:69]
	s_nop 0
	v_cvt_pk_bf16_f32 v13, v14, v15
	global_store_dwordx2 v[6:7], v[12:13], off offset:80
	global_load_dwordx4 v[12:15], v[2:3], off offset:192
	s_nop 0
	global_load_dwordx2 v[68:69], v[4:5], off offset:96
	s_waitcnt vmcnt(1)
	v_pk_mul_f32 v[12:13], v[70:71], v[12:13]
	s_waitcnt vmcnt(0)
	v_lshlrev_b32_e32 v11, 16, v68
	v_mul_f32_e32 v11, 0xbfb8aa3b, v11
	v_exp_f32_e32 v11, v11
	v_lshlrev_b32_e32 v70, 16, v205
	v_and_b32_e32 v71, 0xffff0000, v205
	v_pk_mul_f32 v[70:71], v[0:1], v[70:71] op_sel_hi:[0,1]
	v_add_f32_e32 v11, 1.0, v11
	v_rcp_f32_e32 v74, v11
	v_and_b32_e32 v11, 0xffff0000, v68
	v_mul_f32_e32 v11, 0xbfb8aa3b, v11
	v_exp_f32_e32 v11, v11
	v_pk_mul_f32 v[14:15], v[70:71], v[14:15]
	v_lshlrev_b32_e32 v70, 16, v206
	v_and_b32_e32 v71, 0xffff0000, v206
	v_add_f32_e32 v11, 1.0, v11
	v_rcp_f32_e32 v75, v11
	v_lshlrev_b32_e32 v11, 16, v69
	v_mul_f32_e32 v11, 0xbfb8aa3b, v11
	v_exp_f32_e32 v11, v11
	v_pk_mul_f32 v[12:13], v[12:13], v[74:75]
	v_pk_mul_f32 v[70:71], v[0:1], v[70:71] op_sel_hi:[0,1]
	v_cvt_pk_bf16_f32 v12, v12, v13
	v_add_f32_e32 v11, 1.0, v11
	v_rcp_f32_e32 v68, v11
	v_and_b32_e32 v11, 0xffff0000, v69
	v_mul_f32_e32 v11, 0xbfb8aa3b, v11
	v_exp_f32_e32 v11, v11
	s_nop 0
	v_add_f32_e32 v11, 1.0, v11
	v_rcp_f32_e32 v69, v11
	s_nop 0
	v_pk_mul_f32 v[14:15], v[14:15], v[68:69]
	s_nop 0
	v_cvt_pk_bf16_f32 v13, v14, v15
	global_store_dwordx2 v[6:7], v[12:13], off offset:96
	global_load_dwordx4 v[12:15], v[2:3], off offset:224
	s_nop 0
	global_load_dwordx2 v[68:69], v[4:5], off offset:112
	s_waitcnt vmcnt(1)
	v_pk_mul_f32 v[12:13], v[70:71], v[12:13]
	s_waitcnt vmcnt(0)
	v_lshlrev_b32_e32 v11, 16, v68
	v_mul_f32_e32 v11, 0xbfb8aa3b, v11
	v_exp_f32_e32 v11, v11
	v_lshlrev_b32_e32 v70, 16, v207
	v_and_b32_e32 v71, 0xffff0000, v207
	v_pk_mul_f32 v[70:71], v[0:1], v[70:71] op_sel_hi:[0,1]
	v_add_f32_e32 v11, 1.0, v11
	v_rcp_f32_e32 v74, v11
	v_and_b32_e32 v11, 0xffff0000, v68
	v_mul_f32_e32 v11, 0xbfb8aa3b, v11
	v_exp_f32_e32 v11, v11
	v_pk_mul_f32 v[14:15], v[70:71], v[14:15]
	v_lshlrev_b32_e32 v70, 16, v208
	v_and_b32_e32 v71, 0xffff0000, v208
	v_add_f32_e32 v11, 1.0, v11
	v_rcp_f32_e32 v75, v11
	v_lshlrev_b32_e32 v11, 16, v69
	v_mul_f32_e32 v11, 0xbfb8aa3b, v11
	v_exp_f32_e32 v11, v11
	v_pk_mul_f32 v[12:13], v[12:13], v[74:75]
	v_pk_mul_f32 v[70:71], v[0:1], v[70:71] op_sel_hi:[0,1]
	v_cvt_pk_bf16_f32 v12, v12, v13
	v_add_f32_e32 v11, 1.0, v11
	v_rcp_f32_e32 v68, v11
	v_and_b32_e32 v11, 0xffff0000, v69
	v_mul_f32_e32 v11, 0xbfb8aa3b, v11
	v_exp_f32_e32 v11, v11
	s_nop 0
	v_add_f32_e32 v11, 1.0, v11
	v_rcp_f32_e32 v69, v11
	s_nop 0
	v_pk_mul_f32 v[14:15], v[14:15], v[68:69]
	s_nop 0
	v_cvt_pk_bf16_f32 v13, v14, v15
	global_store_dwordx2 v[6:7], v[12:13], off offset:112
	global_load_dwordx4 v[12:15], v[2:3], off offset:256
	s_nop 0
	global_load_dwordx2 v[68:69], v[4:5], off offset:128
	s_waitcnt vmcnt(1)
	v_pk_mul_f32 v[12:13], v[70:71], v[12:13]
	s_waitcnt vmcnt(0)
	v_lshlrev_b32_e32 v11, 16, v68
	v_mul_f32_e32 v11, 0xbfb8aa3b, v11
	v_exp_f32_e32 v11, v11
	v_lshlrev_b32_e32 v70, 16, v209
	v_and_b32_e32 v71, 0xffff0000, v209
	v_pk_mul_f32 v[70:71], v[0:1], v[70:71] op_sel_hi:[0,1]
	v_add_f32_e32 v11, 1.0, v11
	v_rcp_f32_e32 v74, v11
	v_and_b32_e32 v11, 0xffff0000, v68
	v_mul_f32_e32 v11, 0xbfb8aa3b, v11
	v_exp_f32_e32 v11, v11
	v_pk_mul_f32 v[14:15], v[70:71], v[14:15]
	v_lshlrev_b32_e32 v70, 16, v210
	v_and_b32_e32 v71, 0xffff0000, v210
	v_add_f32_e32 v11, 1.0, v11
	v_rcp_f32_e32 v75, v11
	v_lshlrev_b32_e32 v11, 16, v69
	v_mul_f32_e32 v11, 0xbfb8aa3b, v11
	v_exp_f32_e32 v11, v11
	v_pk_mul_f32 v[12:13], v[12:13], v[74:75]
	v_pk_mul_f32 v[70:71], v[0:1], v[70:71] op_sel_hi:[0,1]
	v_cvt_pk_bf16_f32 v12, v12, v13
	v_add_f32_e32 v11, 1.0, v11
	v_rcp_f32_e32 v68, v11
	v_and_b32_e32 v11, 0xffff0000, v69
	v_mul_f32_e32 v11, 0xbfb8aa3b, v11
	v_exp_f32_e32 v11, v11
	s_nop 0
	v_add_f32_e32 v11, 1.0, v11
	v_rcp_f32_e32 v69, v11
	s_nop 0
	v_pk_mul_f32 v[14:15], v[14:15], v[68:69]
	s_nop 0
	v_cvt_pk_bf16_f32 v13, v14, v15
	global_store_dwordx2 v[6:7], v[12:13], off offset:128
	global_load_dwordx4 v[12:15], v[2:3], off offset:288
	s_nop 0
	global_load_dwordx2 v[68:69], v[4:5], off offset:144
	s_waitcnt vmcnt(1)
	v_pk_mul_f32 v[12:13], v[70:71], v[12:13]
	s_waitcnt vmcnt(0)
	v_lshlrev_b32_e32 v11, 16, v68
	v_mul_f32_e32 v11, 0xbfb8aa3b, v11
	v_exp_f32_e32 v11, v11
	v_lshlrev_b32_e32 v70, 16, v81
	v_and_b32_e32 v71, 0xffff0000, v81
	v_pk_mul_f32 v[70:71], v[0:1], v[70:71] op_sel_hi:[0,1]
	v_add_f32_e32 v11, 1.0, v11
	v_rcp_f32_e32 v74, v11
	v_and_b32_e32 v11, 0xffff0000, v68
	v_mul_f32_e32 v11, 0xbfb8aa3b, v11
	v_exp_f32_e32 v11, v11
	v_pk_mul_f32 v[14:15], v[70:71], v[14:15]
	v_lshlrev_b32_e32 v70, 16, v79
	v_and_b32_e32 v71, 0xffff0000, v79
	v_add_f32_e32 v11, 1.0, v11
	v_rcp_f32_e32 v75, v11
	v_lshlrev_b32_e32 v11, 16, v69
	v_mul_f32_e32 v11, 0xbfb8aa3b, v11
	v_exp_f32_e32 v11, v11
	v_pk_mul_f32 v[12:13], v[12:13], v[74:75]
	v_pk_mul_f32 v[70:71], v[0:1], v[70:71] op_sel_hi:[0,1]
	v_cvt_pk_bf16_f32 v12, v12, v13
	v_add_f32_e32 v11, 1.0, v11
	v_rcp_f32_e32 v68, v11
	v_and_b32_e32 v11, 0xffff0000, v69
	v_mul_f32_e32 v11, 0xbfb8aa3b, v11
	v_exp_f32_e32 v11, v11
	s_nop 0
	v_add_f32_e32 v11, 1.0, v11
	v_rcp_f32_e32 v69, v11
	s_nop 0
	v_pk_mul_f32 v[14:15], v[14:15], v[68:69]
	s_nop 0
	v_cvt_pk_bf16_f32 v13, v14, v15
	global_store_dwordx2 v[6:7], v[12:13], off offset:144
	global_load_dwordx4 v[12:15], v[2:3], off offset:320
	s_nop 0
	global_load_dwordx2 v[68:69], v[4:5], off offset:160
	s_waitcnt vmcnt(1)
	v_pk_mul_f32 v[12:13], v[70:71], v[12:13]
	s_waitcnt vmcnt(0)
	v_lshlrev_b32_e32 v11, 16, v68
	v_mul_f32_e32 v11, 0xbfb8aa3b, v11
	v_exp_f32_e32 v11, v11
	v_lshlrev_b32_e32 v70, 16, v78
	v_and_b32_e32 v71, 0xffff0000, v78
	v_pk_mul_f32 v[70:71], v[0:1], v[70:71] op_sel_hi:[0,1]
	v_add_f32_e32 v11, 1.0, v11
	v_rcp_f32_e32 v74, v11
	v_and_b32_e32 v11, 0xffff0000, v68
	v_mul_f32_e32 v11, 0xbfb8aa3b, v11
	v_exp_f32_e32 v11, v11
	v_pk_mul_f32 v[14:15], v[70:71], v[14:15]
	v_lshlrev_b32_e32 v70, 16, v77
	v_and_b32_e32 v71, 0xffff0000, v77
	v_add_f32_e32 v11, 1.0, v11
	v_rcp_f32_e32 v75, v11
	v_lshlrev_b32_e32 v11, 16, v69
	v_mul_f32_e32 v11, 0xbfb8aa3b, v11
	v_exp_f32_e32 v11, v11
	v_pk_mul_f32 v[12:13], v[12:13], v[74:75]
	v_pk_mul_f32 v[70:71], v[0:1], v[70:71] op_sel_hi:[0,1]
	v_cvt_pk_bf16_f32 v12, v12, v13
	v_add_f32_e32 v11, 1.0, v11
	v_rcp_f32_e32 v68, v11
	v_and_b32_e32 v11, 0xffff0000, v69
	v_mul_f32_e32 v11, 0xbfb8aa3b, v11
	v_exp_f32_e32 v11, v11
	s_nop 0
	v_add_f32_e32 v11, 1.0, v11
	v_rcp_f32_e32 v69, v11
	s_nop 0
	v_pk_mul_f32 v[14:15], v[14:15], v[68:69]
	s_nop 0
	v_cvt_pk_bf16_f32 v13, v14, v15
	global_store_dwordx2 v[6:7], v[12:13], off offset:160
	global_load_dwordx4 v[12:15], v[2:3], off offset:352
	s_nop 0
	global_load_dwordx2 v[68:69], v[4:5], off offset:176
	s_waitcnt vmcnt(1)
	v_pk_mul_f32 v[12:13], v[70:71], v[12:13]
	s_waitcnt vmcnt(0)
	v_lshlrev_b32_e32 v11, 16, v68
	v_mul_f32_e32 v11, 0xbfb8aa3b, v11
	v_exp_f32_e32 v11, v11
	v_lshlrev_b32_e32 v70, 16, v76
	v_and_b32_e32 v71, 0xffff0000, v76
	v_pk_mul_f32 v[70:71], v[0:1], v[70:71] op_sel_hi:[0,1]
	v_add_f32_e32 v11, 1.0, v11
	v_rcp_f32_e32 v74, v11
	v_and_b32_e32 v11, 0xffff0000, v68
	v_mul_f32_e32 v11, 0xbfb8aa3b, v11
	v_exp_f32_e32 v11, v11
	v_pk_mul_f32 v[14:15], v[70:71], v[14:15]
	v_lshlrev_b32_e32 v70, 16, v67
	v_and_b32_e32 v71, 0xffff0000, v67
	v_add_f32_e32 v11, 1.0, v11
	v_rcp_f32_e32 v75, v11
	v_lshlrev_b32_e32 v11, 16, v69
	v_mul_f32_e32 v11, 0xbfb8aa3b, v11
	v_exp_f32_e32 v11, v11
	v_pk_mul_f32 v[12:13], v[12:13], v[74:75]
	v_pk_mul_f32 v[70:71], v[0:1], v[70:71] op_sel_hi:[0,1]
	v_cvt_pk_bf16_f32 v12, v12, v13
	v_add_f32_e32 v11, 1.0, v11
	v_rcp_f32_e32 v68, v11
	v_and_b32_e32 v11, 0xffff0000, v69
	v_mul_f32_e32 v11, 0xbfb8aa3b, v11
	v_exp_f32_e32 v11, v11
	s_nop 0
	v_add_f32_e32 v11, 1.0, v11
	v_rcp_f32_e32 v69, v11
	s_nop 0
	v_pk_mul_f32 v[14:15], v[14:15], v[68:69]
	s_nop 0
	v_cvt_pk_bf16_f32 v13, v14, v15
	global_store_dwordx2 v[6:7], v[12:13], off offset:176
	global_load_dwordx4 v[12:15], v[2:3], off offset:384
	s_nop 0
	global_load_dwordx2 v[68:69], v[4:5], off offset:192
	s_waitcnt vmcnt(1)
	v_pk_mul_f32 v[12:13], v[70:71], v[12:13]
	s_waitcnt vmcnt(0)
	v_lshlrev_b32_e32 v11, 16, v68
	v_mul_f32_e32 v11, 0xbfb8aa3b, v11
	v_exp_f32_e32 v11, v11
	v_lshlrev_b32_e32 v70, 16, v66
	v_and_b32_e32 v71, 0xffff0000, v66
	v_pk_mul_f32 v[66:67], v[0:1], v[70:71] op_sel_hi:[0,1]
	v_add_f32_e32 v11, 1.0, v11
	v_rcp_f32_e32 v74, v11
	v_and_b32_e32 v11, 0xffff0000, v68
	v_mul_f32_e32 v11, 0xbfb8aa3b, v11
	v_exp_f32_e32 v11, v11
	v_pk_mul_f32 v[14:15], v[66:67], v[14:15]
	v_add_f32_e32 v11, 1.0, v11
	v_rcp_f32_e32 v75, v11
	v_lshlrev_b32_e32 v11, 16, v69
	v_mul_f32_e32 v11, 0xbfb8aa3b, v11
	v_exp_f32_e32 v11, v11
	v_pk_mul_f32 v[12:13], v[12:13], v[74:75]
	v_add_f32_e32 v11, 1.0, v11
	v_rcp_f32_e32 v68, v11
	v_and_b32_e32 v11, 0xffff0000, v69
	v_mul_f32_e32 v11, 0xbfb8aa3b, v11
	v_exp_f32_e32 v11, v11
	v_cvt_pk_bf16_f32 v12, v12, v13
	v_add_f32_e32 v11, 1.0, v11
	v_rcp_f32_e32 v69, v11
	s_nop 0
	v_pk_mul_f32 v[14:15], v[14:15], v[68:69]
	s_nop 0
	v_cvt_pk_bf16_f32 v13, v14, v15
	global_store_dwordx2 v[6:7], v[12:13], off offset:192
	global_load_dwordx4 v[12:15], v[2:3], off offset:416
	s_nop 0
	global_load_dwordx2 v[66:67], v[4:5], off offset:208
	v_lshlrev_b32_e32 v68, 16, v65
	v_and_b32_e32 v69, 0xffff0000, v65
	v_pk_mul_f32 v[68:69], v[0:1], v[68:69] op_sel_hi:[0,1]
	s_waitcnt vmcnt(1)
	v_pk_mul_f32 v[12:13], v[68:69], v[12:13]
	s_waitcnt vmcnt(0)
	v_lshlrev_b32_e32 v11, 16, v66
	v_mul_f32_e32 v11, 0xbfb8aa3b, v11
	v_exp_f32_e32 v11, v11
	v_lshlrev_b32_e32 v68, 16, v64
	v_and_b32_e32 v69, 0xffff0000, v64
	v_pk_mul_f32 v[64:65], v[0:1], v[68:69] op_sel_hi:[0,1]
	v_add_f32_e32 v11, 1.0, v11
	v_rcp_f32_e32 v70, v11
	v_and_b32_e32 v11, 0xffff0000, v66
	v_mul_f32_e32 v11, 0xbfb8aa3b, v11
	v_exp_f32_e32 v11, v11
	v_pk_mul_f32 v[14:15], v[64:65], v[14:15]
	v_add_f32_e32 v11, 1.0, v11
	v_rcp_f32_e32 v71, v11
	v_lshlrev_b32_e32 v11, 16, v67
	v_mul_f32_e32 v11, 0xbfb8aa3b, v11
	v_exp_f32_e32 v11, v11
	v_pk_mul_f32 v[12:13], v[12:13], v[70:71]
	v_add_f32_e32 v11, 1.0, v11
	v_rcp_f32_e32 v66, v11
	v_and_b32_e32 v11, 0xffff0000, v67
	v_mul_f32_e32 v11, 0xbfb8aa3b, v11
	v_exp_f32_e32 v11, v11
	v_cvt_pk_bf16_f32 v12, v12, v13
	v_add_f32_e32 v11, 1.0, v11
	v_rcp_f32_e32 v67, v11
	s_nop 0
	v_pk_mul_f32 v[14:15], v[14:15], v[66:67]
	s_nop 0
	v_cvt_pk_bf16_f32 v13, v14, v15
	global_store_dwordx2 v[6:7], v[12:13], off offset:208
	global_load_dwordx4 v[12:15], v[2:3], off offset:448
	s_nop 0
	global_load_dwordx2 v[64:65], v[4:5], off offset:224
	v_lshlrev_b32_e32 v66, 16, v9
	v_and_b32_e32 v67, 0xffff0000, v9
	v_pk_mul_f32 v[66:67], v[0:1], v[66:67] op_sel_hi:[0,1]
	s_waitcnt vmcnt(1)
	v_pk_mul_f32 v[12:13], v[66:67], v[12:13]
	s_waitcnt vmcnt(0)
	v_and_b32_e32 v9, 0xffff0000, v64
	v_mul_f32_e32 v9, 0xbfb8aa3b, v9
	v_exp_f32_e32 v9, v9
	v_lshlrev_b32_e32 v11, 16, v64
	v_lshlrev_b32_e32 v66, 16, v8
	v_and_b32_e32 v67, 0xffff0000, v8
	v_add_f32_e32 v9, 1.0, v9
	v_rcp_f32_e32 v69, v9
	v_lshlrev_b32_e32 v9, 16, v65
	v_and_b32_e32 v8, 0xffff0000, v65
	v_mul_f32_e32 v11, 0xbfb8aa3b, v11
	v_mul_f32_e32 v9, 0xbfb8aa3b, v9
	v_mul_f32_e32 v8, 0xbfb8aa3b, v8
	v_exp_f32_e32 v11, v11
	v_exp_f32_e32 v9, v9
	v_exp_f32_e32 v8, v8
	v_add_f32_e32 v11, 1.0, v11
	v_add_f32_e32 v9, 1.0, v9
	v_add_f32_e32 v8, 1.0, v8
	v_rcp_f32_e32 v68, v11
	v_rcp_f32_e32 v64, v9
	v_rcp_f32_e32 v65, v8
	v_pk_mul_f32 v[8:9], v[0:1], v[66:67] op_sel_hi:[0,1]
	v_pk_mul_f32 v[8:9], v[8:9], v[14:15]
	v_pk_mul_f32 v[12:13], v[12:13], v[68:69]
	v_pk_mul_f32 v[8:9], v[8:9], v[64:65]
	v_cvt_pk_bf16_f32 v12, v12, v13
	v_cvt_pk_bf16_f32 v13, v8, v9
	global_store_dwordx2 v[6:7], v[12:13], off offset:224
	global_load_dwordx4 v[12:15], v[2:3], off offset:480
	s_nop 0
	global_load_dwordx2 v[2:3], v[4:5], off offset:240
	v_lshlrev_b32_e32 v4, 16, v1
	s_waitcnt vmcnt(0)
	v_lshlrev_b32_e32 v5, 16, v2
	v_mul_f32_e32 v5, 0xbfb8aa3b, v5
	v_exp_f32_e32 v5, v5
	s_nop 0
	v_add_f32_e32 v5, 1.0, v5
	v_rcp_f32_e32 v8, v5
	v_and_b32_e32 v5, 0xffff0000, v1
	v_and_b32_e32 v1, 0xffff0000, v2
	v_mul_f32_e32 v1, 0xbfb8aa3b, v1
	v_exp_f32_e32 v1, v1
	s_nop 0
	v_add_f32_e32 v1, 1.0, v1
	v_rcp_f32_e32 v9, v1
	v_pk_mul_f32 v[4:5], v[0:1], v[4:5] op_sel_hi:[0,1]
	v_lshlrev_b32_e32 v1, 16, v3
	v_mul_f32_e32 v1, 0xbfb8aa3b, v1
	v_exp_f32_e32 v1, v1
	v_pk_mul_f32 v[4:5], v[4:5], v[12:13]
	v_add_f32_e32 v1, 1.0, v1
	v_rcp_f32_e32 v2, v1
	v_and_b32_e32 v1, 0xffff0000, v3
	v_mul_f32_e32 v1, 0xbfb8aa3b, v1
	v_exp_f32_e32 v1, v1
	v_pk_mul_f32 v[4:5], v[4:5], v[8:9]
	v_lshlrev_b32_e32 v8, 16, v10
	v_and_b32_e32 v9, 0xffff0000, v10
	v_add_f32_e32 v1, 1.0, v1
	v_rcp_f32_e32 v3, v1
	v_pk_mul_f32 v[0:1], v[0:1], v[8:9] op_sel_hi:[0,1]
	v_pk_mul_f32 v[0:1], v[0:1], v[14:15]
	s_nop 0
	v_pk_mul_f32 v[0:1], v[0:1], v[2:3]
	v_cvt_pk_bf16_f32 v2, v4, v5
	v_cvt_pk_bf16_f32 v3, v0, v1
	v_lshlrev_b64 v[0:1], 10, v[114:115]
	global_store_dwordx2 v[6:7], v[2:3], off offset:240
	v_lshl_add_u64 v[8:9], v[72:73], 0, v[0:1]
	global_load_dwordx4 v[64:67], v[8:9], off
	global_load_dwordx4 v[80:83], v[132:133], off offset:16
	global_load_dwordx4 v[84:87], v[132:133], off
	s_waitcnt vmcnt(2)
	v_and_b32_e32 v0, 0xffff0000, v64
	v_lshlrev_b32_e32 v146, 16, v64
	s_waitcnt vmcnt(0)
	v_mul_f32_e32 v148, v85, v0
	v_lshlrev_b32_e32 v0, 16, v67
	v_mul_f32_e32 v136, v82, v0
	v_and_b32_e32 v0, 0xffff0000, v67
	v_mul_f32_e32 v82, v83, v0
	global_load_dwordx4 v[68:71], v[8:9], off offset:32
	global_load_dwordx4 v[0:3], v[132:133], off offset:80
	global_load_dwordx4 v[4:7], v[132:133], off offset:64
	v_lshlrev_b32_e32 v144, 16, v65
	v_and_b32_e32 v142, 0xffff0000, v65
	v_lshlrev_b32_e32 v140, 16, v66
	v_and_b32_e32 v138, 0xffff0000, v66
	s_waitcnt vmcnt(2)
	v_and_b32_e32 v11, 0xffff0000, v68
	v_lshlrev_b32_e32 v10, 16, v68
	s_waitcnt vmcnt(0)
	v_mul_f32_e32 v12, v5, v11
	v_pk_fma_f32 v[4:5], v[4:5], v[10:11], v[12:13] op_sel_hi:[1,1,0]
	v_and_b32_e32 v11, 0xffff0000, v69
	v_lshlrev_b32_e32 v10, 16, v69
	v_pk_fma_f32 v[4:5], v[6:7], v[10:11], v[4:5]
	v_mul_f32_e32 v6, v7, v11
	v_pk_add_f32 v[4:5], v[6:7], v[4:5] op_sel_hi:[0,1]
	v_and_b32_e32 v7, 0xffff0000, v70
	v_lshlrev_b32_e32 v6, 16, v70
	v_pk_fma_f32 v[4:5], v[0:1], v[6:7], v[4:5]
	v_mul_f32_e32 v0, v1, v7
	v_pk_add_f32 v[0:1], v[0:1], v[4:5] op_sel_hi:[0,1]
	v_and_b32_e32 v5, 0xffff0000, v71
	v_lshlrev_b32_e32 v4, 16, v71
	v_pk_fma_f32 v[0:1], v[2:3], v[4:5], v[0:1]
	v_mul_f32_e32 v2, v3, v5
	v_pk_add_f32 v[150:151], v[2:3], v[0:1] op_sel_hi:[0,1]
	global_load_dwordx4 v[72:75], v[8:9], off offset:64
	global_load_dwordx4 v[0:3], v[132:133], off offset:144
	global_load_dwordx4 v[4:7], v[132:133], off offset:128
	s_waitcnt vmcnt(2)
	v_and_b32_e32 v11, 0xffff0000, v72
	v_lshlrev_b32_e32 v10, 16, v72
	s_waitcnt vmcnt(0)
	v_mul_f32_e32 v12, v5, v11
	v_pk_fma_f32 v[4:5], v[4:5], v[10:11], v[12:13] op_sel_hi:[1,1,0]
	v_and_b32_e32 v11, 0xffff0000, v73
	v_lshlrev_b32_e32 v10, 16, v73
	v_pk_fma_f32 v[4:5], v[6:7], v[10:11], v[4:5]
	v_mul_f32_e32 v6, v7, v11
	v_pk_add_f32 v[4:5], v[6:7], v[4:5] op_sel_hi:[0,1]
	v_and_b32_e32 v7, 0xffff0000, v74
	v_lshlrev_b32_e32 v6, 16, v74
	v_pk_fma_f32 v[4:5], v[0:1], v[6:7], v[4:5]
	v_mul_f32_e32 v0, v1, v7
	v_pk_add_f32 v[0:1], v[0:1], v[4:5] op_sel_hi:[0,1]
	v_and_b32_e32 v5, 0xffff0000, v75
	v_lshlrev_b32_e32 v4, 16, v75
	v_pk_fma_f32 v[0:1], v[2:3], v[4:5], v[0:1]
	v_mul_f32_e32 v2, v3, v5
	v_pk_add_f32 v[152:153], v[2:3], v[0:1] op_sel_hi:[0,1]
	global_load_dwordx4 v[76:79], v[8:9], off offset:96
	global_load_dwordx4 v[0:3], v[132:133], off offset:208
	global_load_dwordx4 v[4:7], v[132:133], off offset:192
	global_load_dwordx4 v[174:177], v[134:135], off offset:32
	s_waitcnt vmcnt(3)
	v_and_b32_e32 v9, 0xffff0000, v76
	v_lshlrev_b32_e32 v8, 16, v76
	s_waitcnt vmcnt(1)
	v_mul_f32_e32 v10, v5, v9
	v_pk_fma_f32 v[4:5], v[4:5], v[8:9], v[10:11] op_sel_hi:[1,1,0]
	v_and_b32_e32 v9, 0xffff0000, v77
	v_lshlrev_b32_e32 v8, 16, v77
	v_pk_fma_f32 v[4:5], v[6:7], v[8:9], v[4:5]
	v_mul_f32_e32 v6, v7, v9
	v_pk_add_f32 v[4:5], v[6:7], v[4:5] op_sel_hi:[0,1]
	v_and_b32_e32 v7, 0xffff0000, v78
	v_lshlrev_b32_e32 v6, 16, v78
	v_pk_fma_f32 v[4:5], v[0:1], v[6:7], v[4:5]
	v_mul_f32_e32 v0, v1, v7
	v_pk_add_f32 v[0:1], v[0:1], v[4:5] op_sel_hi:[0,1]
	v_and_b32_e32 v5, 0xffff0000, v79
	v_lshlrev_b32_e32 v4, 16, v79
	v_pk_fma_f32 v[0:1], v[2:3], v[4:5], v[0:1]
	v_mul_f32_e32 v2, v3, v5
	v_pk_add_f32 v[132:133], v[2:3], v[0:1] op_sel_hi:[0,1]
	global_load_dwordx4 v[0:3], v[134:135], off
	s_waitcnt vmcnt(0)
	v_mfma_f32_32x32x16_bf16 v[0:15], v[0:3], v[64:67], 0
	v_mfma_f32_32x32x16_bf16 v[0:15], v[174:177], v[68:71], v[0:15]
	global_load_dwordx4 v[174:177], v[134:135], off offset:64
	s_waitcnt vmcnt(0)
	v_mfma_f32_32x32x16_bf16 v[0:15], v[174:177], v[72:75], v[0:15]
	global_load_dwordx4 v[174:177], v[134:135], off offset:96
	s_waitcnt vmcnt(0)
	v_mfma_f32_32x32x16_bf16 v[0:15], v[174:177], v[76:79], v[0:15]
	s_nop 11
	v_mul_f32_e32 v126, v60, v0
	v_fma_f32 v83, v60, v0, 0
	v_sub_f32_e32 v0, v61, v119
	v_exp_f32_e32 v0, v0
	s_nop 0
	v_cndmask_b32_e64 v0, 0, v0, s[2:3]
	v_mul_f32_e32 v134, v0, v1
	v_fmac_f32_e32 v83, v0, v1
	v_sub_f32_e32 v1, v63, v119
	v_exp_f32_e32 v1, v1
	v_sub_f32_e32 v0, v62, v119
	v_exp_f32_e32 v0, v0
	v_readlane_b32 s2, v254, 23
	v_readlane_b32 s3, v254, 24
	s_nop 1
	v_cndmask_b32_e64 v1, v1, 0, s[2:3]
	v_readlane_b32 s2, v254, 25
	v_readlane_b32 s3, v254, 26
	s_nop 1
	v_cndmask_b32_e64 v0, v0, 0, s[2:3]
	v_pk_mul_f32 v[60:61], v[0:1], v[2:3]
	v_sub_f32_e32 v1, v53, v119
	v_add_f32_e32 v0, v60, v83
	v_exp_f32_e32 v1, v1
	v_add_f32_e32 v2, v61, v0
	v_sub_f32_e32 v0, v52, v119
	v_exp_f32_e32 v0, v0
	v_readlane_b32 s2, v254, 33
	v_readlane_b32 s3, v254, 34
	s_nop 1
	v_cndmask_b32_e64 v1, v1, 0, s[2:3]
	v_readlane_b32 s2, v254, 29
	v_readlane_b32 s3, v254, 30
	s_nop 1
	v_cndmask_b32_e64 v0, v0, 0, s[2:3]
	v_pk_mul_f32 v[52:53], v[0:1], v[4:5]
	v_sub_f32_e32 v1, v55, v119
	v_add_f32_e32 v0, v52, v2
	v_exp_f32_e32 v1, v1
	v_add_f32_e32 v2, v53, v0
	v_sub_f32_e32 v0, v54, v119
	v_exp_f32_e32 v0, v0
	v_readlane_b32 s2, v254, 31
	v_readlane_b32 s3, v254, 32
	s_nop 1
	v_cndmask_b32_e64 v1, v1, 0, s[2:3]
	v_readlane_b32 s2, v254, 35
	v_readlane_b32 s3, v254, 36
	s_nop 1
	v_cndmask_b32_e64 v0, v0, 0, s[2:3]
	v_pk_mul_f32 v[54:55], v[0:1], v[6:7]
	v_readlane_b32 s2, v254, 37
	v_add_f32_e32 v0, v54, v2
	v_add_f32_e32 v2, v55, v0
	v_sub_f32_e32 v0, v56, v119
	v_exp_f32_e32 v0, v0
	v_readlane_b32 s3, v254, 38
	v_sub_f32_e32 v1, v59, v119
	v_exp_f32_e32 v1, v1
	v_cndmask_b32_e64 v0, v0, 0, s[2:3]
	v_mul_f32_e32 v62, v0, v8
	v_fmac_f32_e32 v2, v0, v8
	v_sub_f32_e32 v0, v57, v119
	v_exp_f32_e32 v0, v0
	v_readlane_b32 s2, v254, 49
	v_readlane_b32 s3, v254, 50
	s_nop 1
	v_cndmask_b32_e64 v0, 0, v0, s[2:3]
	v_mul_f32_e32 v63, v0, v9
	v_fmac_f32_e32 v2, v0, v9
	v_sub_f32_e32 v0, v58, v119
	v_exp_f32_e32 v0, v0
	v_readlane_b32 s2, v254, 51
	v_readlane_b32 s3, v254, 52
	s_nop 1
	v_cndmask_b32_e64 v1, v1, 0, s[2:3]
	v_readlane_b32 s2, v254, 15
	v_readlane_b32 s3, v254, 16
	s_nop 1
	v_cndmask_b32_e64 v0, v0, 0, s[2:3]
	v_pk_mul_f32 v[56:57], v[0:1], v[10:11]
	v_sub_f32_e32 v1, v49, v119
	v_add_f32_e32 v0, v56, v2
	v_exp_f32_e32 v1, v1
	v_add_f32_e32 v2, v57, v0
	v_sub_f32_e32 v0, v48, v119
	v_exp_f32_e32 v0, v0
	v_readlane_b32 s2, v255, 55
	v_readlane_b32 s3, v255, 56
	s_nop 1
	v_cndmask_b32_e64 v1, v1, 0, s[2:3]
	v_readlane_b32 s2, v255, 57
	v_readlane_b32 s3, v255, 58
	s_nop 1
	v_cndmask_b32_e64 v0, v0, 0, s[2:3]
	v_pk_mul_f32 v[48:49], v[0:1], v[12:13]
	v_sub_f32_e32 v1, v51, v119
	v_add_f32_e32 v0, v48, v2
	v_exp_f32_e32 v1, v1
	v_add_f32_e32 v2, v49, v0
	v_sub_f32_e32 v0, v50, v119
	v_exp_f32_e32 v0, v0
	v_readlane_b32 s2, v255, 59
	v_readlane_b32 s3, v255, 60
	s_nop 1
	v_cndmask_b32_e64 v1, v1, 0, s[2:3]
	v_readlane_b32 s2, v255, 61
	v_readlane_b32 s3, v255, 62
	s_nop 1
	v_cndmask_b32_e64 v0, v0, 0, s[2:3]
	v_pk_mul_f32 v[50:51], v[0:1], v[14:15]
	v_mov_b32_e32 v1, s67
	v_add_f32_e32 v0, v50, v2
	v_add_f32_e32 v149, v51, v0
	v_or_b32_e32 v0, s66, v106
	v_lshlrev_b64 v[0:1], 10, v[0:1]
	v_lshl_add_u64 v[58:59], v[120:121], 0, v[0:1]
	global_load_dwordx4 v[0:3], v[58:59], off
	global_load_dwordx4 v[174:177], v[58:59], off offset:32
	s_waitcnt vmcnt(1)
	v_mfma_f32_32x32x16_bf16 v[0:15], v[0:3], v[64:67], 0
	s_waitcnt vmcnt(0)
	v_mfma_f32_32x32x16_bf16 v[0:15], v[174:177], v[68:71], v[0:15]
	global_load_dwordx4 v[174:177], v[58:59], off offset:64
	s_waitcnt vmcnt(0)
	v_mfma_f32_32x32x16_bf16 v[0:15], v[174:177], v[72:75], v[0:15]
	global_load_dwordx4 v[174:177], v[58:59], off offset:96
	v_cvt_pk_bf16_f32 v59, v60, v61
	v_cvt_pk_bf16_f32 v60, v52, v53
	v_cvt_pk_bf16_f32 v61, v54, v55
	v_cvt_pk_bf16_f32 v52, v62, v63
	v_cvt_pk_bf16_f32 v53, v56, v57
	v_cvt_pk_bf16_f32 v54, v48, v49
	s_waitcnt vmcnt(0)
	v_mfma_f32_32x32x16_bf16 v[0:15], v[174:177], v[76:79], v[0:15]
	ds_read_b128 v[174:177], v105 offset:17536
	ds_read_b128 v[178:181], v105 offset:17552
	v_cvt_pk_bf16_f32 v55, v50, v51
	s_waitcnt lgkmcnt(1)
	v_sub_f32_e32 v58, v174, v119
	v_exp_f32_e32 v58, v58
	s_nop 5
	v_mov_b32_e32 v85, v5
	v_cndmask_b32_e64 v58, v58, 0, s[18:19]
	v_mul_f32_e32 v135, v0, v58
	v_fmac_f32_e32 v149, v0, v58
	v_sub_f32_e32 v0, v175, v119
	v_exp_f32_e32 v0, v0
	v_cvt_pk_bf16_f32 v58, v126, v134
	v_cndmask_b32_e64 v0, 0, v0, s[20:21]
	v_mul_f32_e32 v170, v1, v0
	v_fmac_f32_e32 v149, v1, v0
	v_sub_f32_e32 v0, v176, v119
	v_exp_f32_e32 v0, v0
	s_nop 0
	v_cndmask_b32_e64 v0, v0, 0, s[22:23]
	v_mul_f32_e32 v171, v2, v0
	v_fmac_f32_e32 v149, v2, v0
	v_sub_f32_e32 v0, v177, v119
	v_exp_f32_e32 v0, v0
	s_nop 0
	v_cndmask_b32_e64 v0, v0, 0, s[24:25]
	v_mul_f32_e32 v182, v3, v0
	v_fmac_f32_e32 v149, v3, v0
	s_waitcnt lgkmcnt(0)
	v_sub_f32_e32 v0, v178, v119
	v_exp_f32_e32 v0, v0
	s_nop 0
	v_cndmask_b32_e64 v0, v0, 0, s[26:27]
	v_mul_f32_e32 v178, v4, v0
	v_fmac_f32_e32 v149, v4, v0
	v_sub_f32_e32 v0, v179, v119
	v_exp_f32_e32 v0, v0
	s_nop 0
	v_cndmask_b32_e64 v147, v0, 0, s[28:29]
	v_sub_f32_e32 v0, v180, v119
	v_exp_f32_e32 v0, v0
	v_pk_mul_f32 v[120:121], v[84:85], v[146:147]
	v_cndmask_b32_e64 v145, v0, 0, s[30:31]
	v_sub_f32_e32 v0, v181, v119
	v_exp_f32_e32 v0, v0
	s_nop 0
	v_cndmask_b32_e64 v143, v0, 0, s[34:35]
	ds_read_b128 v[0:3], v105 offset:17600
	ds_read_b128 v[174:177], v105 offset:17616
	s_waitcnt lgkmcnt(1)
	v_sub_f32_e32 v0, v0, v119
	v_exp_f32_e32 v0, v0
	s_nop 0
	v_cndmask_b32_e64 v141, v0, 0, s[84:85]
	v_sub_f32_e32 v0, v1, v119
	v_exp_f32_e32 v0, v0
	v_sub_f32_e32 v1, v3, v119
	v_exp_f32_e32 v1, v1
	v_mov_b32_e32 v3, v6
	v_cndmask_b32_e64 v139, 0, v0, s[68:69]
	v_sub_f32_e32 v0, v2, v119
	v_exp_f32_e32 v0, v0
	v_cndmask_b32_e64 v1, v1, 0, s[70:71]
	v_mov_b32_e32 v2, v86
	v_cndmask_b32_e64 v0, v0, 0, s[72:73]
	v_pk_mul_f32 v[162:163], v[10:11], v[0:1]
	s_waitcnt lgkmcnt(0)
	v_sub_f32_e32 v0, v174, v119
	v_sub_f32_e32 v1, v175, v119
	v_exp_f32_e32 v0, v0
	v_exp_f32_e32 v1, v1
	v_mov_b32_e32 v137, v162
	v_mov_b32_e32 v83, v163
	v_cndmask_b32_e64 v0, v0, 0, s[76:77]
	v_cndmask_b32_e64 v1, v1, 0, s[74:75]
	v_pk_mul_f32 v[164:165], v[12:13], v[0:1]
	v_sub_f32_e32 v0, v176, v119
	v_sub_f32_e32 v1, v177, v119
	v_exp_f32_e32 v0, v0
	v_exp_f32_e32 v1, v1
	v_mov_b32_e32 v151, v165
	v_cndmask_b32_e64 v0, v0, 0, s[4:5]
	v_cndmask_b32_e64 v1, v1, 0, s[78:79]
	v_pk_mul_f32 v[168:169], v[14:15], v[0:1]
	v_pk_fma_f32 v[0:1], v[84:85], v[146:147], v[148:149]
	v_pk_mul_f32 v[84:85], v[2:3], v[144:145]
	v_pk_fma_f32 v[0:1], v[2:3], v[144:145], v[0:1]
	v_mov_b32_e32 v2, v87
	v_mov_b32_e32 v3, v7
	v_pk_fma_f32 v[0:1], v[2:3], v[142:143], v[0:1]
	v_mov_b32_e32 v2, v80
	v_mov_b32_e32 v3, v8
	v_pk_mul_f32 v[86:87], v[6:7], v[142:143]
	v_pk_mul_f32 v[142:143], v[2:3], v[140:141]
	v_pk_fma_f32 v[0:1], v[2:3], v[140:141], v[0:1]
	v_mov_b32_e32 v2, v81
	v_mov_b32_e32 v3, v9
	v_pk_fma_f32 v[0:1], v[2:3], v[138:139], v[0:1]
	v_mov_b32_e32 v2, v161
	v_pk_add_f32 v[0:1], v[136:137], v[0:1]
	v_mov_b32_e32 v3, v164
	v_pk_add_f32 v[0:1], v[82:83], v[0:1]
	v_mov_b32_e32 v153, v168
	v_pk_add_f32 v[0:1], v[2:3], v[0:1]
	v_mov_b32_e32 v133, v169
	v_pk_add_f32 v[0:1], v[150:151], v[0:1]
	global_load_dwordx4 v[80:83], v[124:125], off offset:32
	v_pk_add_f32 v[0:1], v[152:153], v[0:1]
	v_pk_mul_f32 v[140:141], v[8:9], v[138:139]
	v_pk_add_f32 v[0:1], v[132:133], v[0:1]
	ds_bpermute_b32 v2, v159, v0
	ds_bpermute_b32 v3, v159, v1
	v_cvt_pk_bf16_f32 v84, v143, v141
	v_cvt_pk_bf16_f32 v86, v164, v165
	s_waitcnt lgkmcnt(0)
	v_pk_add_f32 v[0:1], v[0:1], v[2:3]
	s_nop 0
	v_fmac_f32_e32 v1, v118, v0
	v_add_f32_e32 v0, v119, v127
	v_exp_f32_e64 v0, -v0
	s_nop 0
	v_max_f32_e64 v0, |v1|, v0
	v_div_scale_f32 v1, s[2:3], v0, v0, 1.0
	v_rcp_f32_e32 v2, v1
	s_nop 0
	v_fma_f32 v3, -v1, v2, 1.0
	v_fmac_f32_e32 v2, v3, v2
	v_div_scale_f32 v3, vcc, 1.0, v0, 1.0
	v_mul_f32_e32 v4, v3, v2
	v_fma_f32 v5, -v1, v4, v3
	v_fmac_f32_e32 v4, v5, v2
	v_fma_f32 v1, -v1, v4, v3
	v_div_fmas_f32 v1, v1, v2, v4
	v_div_fixup_f32 v120, v1, v0, 1.0
	global_load_dwordx4 v[0:3], v[124:125], off
	s_waitcnt vmcnt(0)
	v_mfma_f32_32x32x16_bf16 v[0:15], v[0:3], v[64:67], 0
	v_mfma_f32_32x32x16_bf16 v[0:15], v[80:83], v[68:71], v[0:15]
	global_load_dwordx4 v[80:83], v[124:125], off offset:64
	s_waitcnt vmcnt(0)
	v_mfma_f32_32x32x16_bf16 v[0:15], v[80:83], v[72:75], v[0:15]
	global_load_dwordx4 v[80:83], v[124:125], off offset:96
	s_waitcnt vmcnt(0)
	v_mfma_f32_32x32x16_bf16 v[0:15], v[80:83], v[76:79], v[0:15]
	v_cvt_pk_bf16_f32 v80, v135, v170
	v_cvt_pk_bf16_f32 v81, v171, v182
	v_cvt_pk_bf16_f32 v82, v178, v121
	v_cvt_pk_bf16_f32 v83, v85, v87
	v_cvt_pk_bf16_f32 v85, v162, v163
	v_cvt_pk_bf16_f32 v87, v168, v169
	s_nop 5
	v_pk_mul_f32 v[14:15], v[118:119], v[14:15] op_sel_hi:[0,1]
	v_pk_mul_f32 v[12:13], v[118:119], v[12:13] op_sel_hi:[0,1]
	v_pk_mul_f32 v[10:11], v[118:119], v[10:11] op_sel_hi:[0,1]
	v_pk_mul_f32 v[8:9], v[118:119], v[8:9] op_sel_hi:[0,1]
	v_pk_mul_f32 v[6:7], v[118:119], v[6:7] op_sel_hi:[0,1]
	v_pk_mul_f32 v[4:5], v[118:119], v[4:5] op_sel_hi:[0,1]
	v_pk_mul_f32 v[2:3], v[118:119], v[2:3] op_sel_hi:[0,1]
	v_pk_mul_f32 v[0:1], v[118:119], v[0:1] op_sel_hi:[0,1]
	s_nop 1
	v_mfma_f32_32x32x16_bf16 v[0:15], v[40:43], v[58:61], v[0:15]
	ds_read_b64_tr_b16 v[40:41], v173 offset:8704
	ds_read_b64_tr_b16 v[42:43], v173 offset:9792
	v_mfma_f32_32x32x16_bf16 v[0:15], v[44:47], v[52:55], v[0:15]
	s_waitcnt lgkmcnt(0)
	v_mfma_f32_32x32x16_bf16 v[0:15], v[40:43], v[80:83], v[0:15]
	ds_read_b64_tr_b16 v[40:41], v173 offset:13056
	ds_read_b64_tr_b16 v[42:43], v173 offset:14144
	s_waitcnt lgkmcnt(0)
	v_mfma_f32_32x32x16_bf16 v[0:15], v[40:43], v[84:87], v[0:15]
	global_load_dwordx4 v[40:43], v[128:129], off offset:32
	s_nop 10
	v_pk_mul_f32 v[0:1], v[0:1], v[120:121] op_sel_hi:[1,0]
	s_nop 0
	v_pk_mul_f32 v[56:57], v[0:1], v[0:1]
	v_cvt_pk_bf16_f32 v51, v0, v1
	v_pk_mul_f32 v[0:1], v[2:3], v[120:121] op_sel_hi:[1,0]
	s_nop 0
	v_pk_mul_f32 v[62:63], v[0:1], v[0:1]
	v_cvt_pk_bf16_f32 v50, v0, v1
	v_pk_mul_f32 v[0:1], v[4:5], v[120:121] op_sel_hi:[1,0]
	s_nop 0
	v_pk_mul_f32 v[124:125], v[0:1], v[0:1]
	v_cvt_pk_bf16_f32 v49, v0, v1
	v_pk_mul_f32 v[0:1], v[6:7], v[120:121] op_sel_hi:[1,0]
	s_nop 0
	v_pk_mul_f32 v[126:127], v[0:1], v[0:1]
	v_cvt_pk_bf16_f32 v48, v0, v1
	v_pk_mul_f32 v[0:1], v[8:9], v[120:121] op_sel_hi:[1,0]
	s_nop 0
	v_pk_mul_f32 v[132:133], v[0:1], v[0:1]
	v_cvt_pk_bf16_f32 v47, v0, v1
	v_pk_mul_f32 v[0:1], v[10:11], v[120:121] op_sel_hi:[1,0]
	s_nop 0
	v_pk_mul_f32 v[134:135], v[0:1], v[0:1]
	v_cvt_pk_bf16_f32 v46, v0, v1
	v_pk_mul_f32 v[0:1], v[12:13], v[120:121] op_sel_hi:[1,0]
	s_nop 0
	v_pk_mul_f32 v[136:137], v[0:1], v[0:1]
	v_cvt_pk_bf16_f32 v45, v0, v1
	v_pk_mul_f32 v[0:1], v[14:15], v[120:121] op_sel_hi:[1,0]
	s_nop 0
	v_pk_mul_f32 v[138:139], v[0:1], v[0:1]
	v_cvt_pk_bf16_f32 v44, v0, v1
	global_load_dwordx4 v[0:3], v[122:123], off offset:-4096
	s_waitcnt vmcnt(0)
	v_mfma_f32_32x32x16_bf16 v[0:15], v[0:3], v[64:67], 0
	v_mfma_f32_32x32x16_bf16 v[0:15], v[40:43], v[68:71], v[0:15]
	global_load_dwordx4 v[40:43], v[128:129], off offset:64
	s_waitcnt vmcnt(0)
	v_mfma_f32_32x32x16_bf16 v[0:15], v[40:43], v[72:75], v[0:15]
	global_load_dwordx4 v[40:43], v[128:129], off offset:96
	s_waitcnt vmcnt(0)
	v_mfma_f32_32x32x16_bf16 v[0:15], v[40:43], v[76:79], v[0:15]
	s_nop 11
	v_pk_mul_f32 v[14:15], v[118:119], v[14:15] op_sel_hi:[0,1]
	v_pk_mul_f32 v[12:13], v[118:119], v[12:13] op_sel_hi:[0,1]
	v_pk_mul_f32 v[10:11], v[118:119], v[10:11] op_sel_hi:[0,1]
	v_pk_mul_f32 v[8:9], v[118:119], v[8:9] op_sel_hi:[0,1]
	v_pk_mul_f32 v[6:7], v[118:119], v[6:7] op_sel_hi:[0,1]
	v_pk_mul_f32 v[4:5], v[118:119], v[4:5] op_sel_hi:[0,1]
	v_pk_mul_f32 v[2:3], v[118:119], v[2:3] op_sel_hi:[0,1]
	v_pk_mul_f32 v[0:1], v[118:119], v[0:1] op_sel_hi:[0,1]
	s_nop 1
	v_mfma_f32_32x32x16_bf16 v[0:15], v[28:31], v[58:61], v[0:15]
	ds_read_b64_tr_b16 v[28:29], v173 offset:8768
	ds_read_b64_tr_b16 v[30:31], v173 offset:9856
	v_mfma_f32_32x32x16_bf16 v[0:15], v[36:39], v[52:55], v[0:15]
	s_waitcnt lgkmcnt(0)
	v_mfma_f32_32x32x16_bf16 v[0:15], v[28:31], v[80:83], v[0:15]
	ds_read_b64_tr_b16 v[28:29], v173 offset:13120
	ds_read_b64_tr_b16 v[30:31], v173 offset:14208
	s_waitcnt lgkmcnt(0)
	v_mfma_f32_32x32x16_bf16 v[0:15], v[28:31], v[84:87], v[0:15]
	global_load_dwordx4 v[28:31], v[122:123], off offset:32
	s_nop 10
	v_pk_mul_f32 v[0:1], v[120:121], v[0:1] op_sel_hi:[0,1]
	v_pk_mul_f32 v[128:129], v[0:1], v[0:1]
	v_cvt_pk_bf16_f32 v43, v0, v1
	v_pk_mul_f32 v[0:1], v[120:121], v[2:3] op_sel_hi:[0,1]
	v_pk_mul_f32 v[140:141], v[0:1], v[0:1]
	v_cvt_pk_bf16_f32 v42, v0, v1
	v_pk_mul_f32 v[0:1], v[120:121], v[4:5] op_sel_hi:[0,1]
	v_pk_mul_f32 v[142:143], v[0:1], v[0:1]
	v_cvt_pk_bf16_f32 v41, v0, v1
	v_pk_mul_f32 v[0:1], v[120:121], v[6:7] op_sel_hi:[0,1]
	v_pk_mul_f32 v[144:145], v[0:1], v[0:1]
	v_cvt_pk_bf16_f32 v40, v0, v1
	v_pk_mul_f32 v[0:1], v[120:121], v[8:9] op_sel_hi:[0,1]
	v_pk_mul_f32 v[146:147], v[0:1], v[0:1]
	v_cvt_pk_bf16_f32 v39, v0, v1
	v_pk_mul_f32 v[0:1], v[120:121], v[10:11] op_sel_hi:[0,1]
	v_pk_mul_f32 v[148:149], v[0:1], v[0:1]
	v_cvt_pk_bf16_f32 v38, v0, v1
	v_pk_mul_f32 v[0:1], v[120:121], v[12:13] op_sel_hi:[0,1]
	v_pk_mul_f32 v[150:151], v[0:1], v[0:1]
	v_cvt_pk_bf16_f32 v37, v0, v1
	v_pk_mul_f32 v[0:1], v[120:121], v[14:15] op_sel_hi:[0,1]
	v_pk_mul_f32 v[152:153], v[0:1], v[0:1]
	v_cvt_pk_bf16_f32 v36, v0, v1
	global_load_dwordx4 v[0:3], v[130:131], off offset:-4096
	s_waitcnt vmcnt(0)
	v_mfma_f32_32x32x16_bf16 v[0:15], v[0:3], v[64:67], 0
	v_mfma_f32_32x32x16_bf16 v[0:15], v[28:31], v[68:71], v[0:15]
	global_load_dwordx4 v[28:31], v[122:123], off offset:64
	s_waitcnt vmcnt(0)
	v_mfma_f32_32x32x16_bf16 v[0:15], v[28:31], v[72:75], v[0:15]
	global_load_dwordx4 v[28:31], v[122:123], off offset:96
	s_waitcnt vmcnt(0)
	v_mfma_f32_32x32x16_bf16 v[0:15], v[28:31], v[76:79], v[0:15]
	s_nop 11
	v_pk_mul_f32 v[14:15], v[118:119], v[14:15] op_sel_hi:[0,1]
	v_pk_mul_f32 v[12:13], v[118:119], v[12:13] op_sel_hi:[0,1]
	v_pk_mul_f32 v[10:11], v[118:119], v[10:11] op_sel_hi:[0,1]
	v_pk_mul_f32 v[8:9], v[118:119], v[8:9] op_sel_hi:[0,1]
	v_pk_mul_f32 v[6:7], v[118:119], v[6:7] op_sel_hi:[0,1]
	v_pk_mul_f32 v[4:5], v[118:119], v[4:5] op_sel_hi:[0,1]
	v_pk_mul_f32 v[2:3], v[118:119], v[2:3] op_sel_hi:[0,1]
	v_pk_mul_f32 v[0:1], v[118:119], v[0:1] op_sel_hi:[0,1]
	s_nop 1
	v_mfma_f32_32x32x16_bf16 v[0:15], v[16:19], v[58:61], v[0:15]
	ds_read_b64_tr_b16 v[16:17], v173 offset:8832
	ds_read_b64_tr_b16 v[18:19], v173 offset:9920
	v_mfma_f32_32x32x16_bf16 v[0:15], v[24:27], v[52:55], v[0:15]
	s_waitcnt lgkmcnt(0)
	v_mfma_f32_32x32x16_bf16 v[0:15], v[16:19], v[80:83], v[0:15]
	ds_read_b64_tr_b16 v[16:17], v173 offset:13184
	ds_read_b64_tr_b16 v[18:19], v173 offset:14272
	s_waitcnt lgkmcnt(0)
	v_mfma_f32_32x32x16_bf16 v[0:15], v[16:19], v[84:87], v[0:15]
	global_load_dwordx4 v[16:19], v[130:131], off offset:32
	s_nop 10
	v_pk_mul_f32 v[0:1], v[120:121], v[0:1] op_sel_hi:[0,1]
	v_pk_mul_f32 v[122:123], v[0:1], v[0:1]
	v_cvt_pk_bf16_f32 v31, v0, v1
	v_pk_mul_f32 v[0:1], v[120:121], v[2:3] op_sel_hi:[0,1]
	v_pk_mul_f32 v[162:163], v[0:1], v[0:1]
	v_cvt_pk_bf16_f32 v30, v0, v1
	v_pk_mul_f32 v[0:1], v[120:121], v[4:5] op_sel_hi:[0,1]
	v_pk_mul_f32 v[164:165], v[0:1], v[0:1]
	v_cvt_pk_bf16_f32 v29, v0, v1
	v_pk_mul_f32 v[0:1], v[120:121], v[6:7] op_sel_hi:[0,1]
	v_pk_mul_f32 v[168:169], v[0:1], v[0:1]
	v_cvt_pk_bf16_f32 v28, v0, v1
	v_pk_mul_f32 v[0:1], v[120:121], v[8:9] op_sel_hi:[0,1]
	v_pk_mul_f32 v[170:171], v[0:1], v[0:1]
	v_cvt_pk_bf16_f32 v27, v0, v1
	v_pk_mul_f32 v[0:1], v[120:121], v[10:11] op_sel_hi:[0,1]
	v_pk_mul_f32 v[174:175], v[0:1], v[0:1]
	v_cvt_pk_bf16_f32 v26, v0, v1
	v_pk_mul_f32 v[0:1], v[120:121], v[12:13] op_sel_hi:[0,1]
	v_pk_mul_f32 v[176:177], v[0:1], v[0:1]
	v_cvt_pk_bf16_f32 v25, v0, v1
	v_pk_mul_f32 v[0:1], v[120:121], v[14:15] op_sel_hi:[0,1]
	v_pk_mul_f32 v[178:179], v[0:1], v[0:1]
	v_cvt_pk_bf16_f32 v24, v0, v1
	global_load_dwordx4 v[0:3], v[130:131], off
	s_waitcnt vmcnt(0)
	v_mfma_f32_32x32x16_bf16 v[0:15], v[0:3], v[64:67], 0
	v_mfma_f32_32x32x16_bf16 v[0:15], v[16:19], v[68:71], v[0:15]
	global_load_dwordx4 v[16:19], v[130:131], off offset:64
	s_waitcnt vmcnt(0)
	v_mfma_f32_32x32x16_bf16 v[0:15], v[16:19], v[72:75], v[0:15]
	global_load_dwordx4 v[16:19], v[130:131], off offset:96
	s_waitcnt vmcnt(0)
	v_mfma_f32_32x32x16_bf16 v[0:15], v[16:19], v[76:79], v[0:15]
	ds_read_b64_tr_b16 v[16:17], v173 offset:8896
	ds_read_b64_tr_b16 v[18:19], v173 offset:9984
	s_nop 9
	v_pk_mul_f32 v[14:15], v[118:119], v[14:15] op_sel_hi:[0,1]
	v_pk_mul_f32 v[12:13], v[118:119], v[12:13] op_sel_hi:[0,1]
	v_pk_mul_f32 v[10:11], v[118:119], v[10:11] op_sel_hi:[0,1]
	v_pk_mul_f32 v[8:9], v[118:119], v[8:9] op_sel_hi:[0,1]
	v_pk_mul_f32 v[6:7], v[118:119], v[6:7] op_sel_hi:[0,1]
	v_pk_mul_f32 v[4:5], v[118:119], v[4:5] op_sel_hi:[0,1]
	v_pk_mul_f32 v[2:3], v[118:119], v[2:3] op_sel_hi:[0,1]
	v_pk_mul_f32 v[0:1], v[118:119], v[0:1] op_sel_hi:[0,1]
	s_nop 1
	v_mfma_f32_32x32x16_bf16 v[0:15], v[20:23], v[58:61], v[0:15]
	v_mfma_f32_32x32x16_bf16 v[0:15], v[32:35], v[52:55], v[0:15]
	s_waitcnt lgkmcnt(0)
	v_mfma_f32_32x32x16_bf16 v[0:15], v[16:19], v[80:83], v[0:15]
	ds_read_b64_tr_b16 v[16:17], v173 offset:13248
	ds_read_b64_tr_b16 v[18:19], v173 offset:14336
	s_waitcnt lgkmcnt(0)
	v_mfma_f32_32x32x16_bf16 v[0:15], v[16:19], v[84:87], v[0:15]
	s_nop 11
	v_pk_mul_f32 v[0:1], v[120:121], v[0:1] op_sel_hi:[0,1]
	v_pk_mul_f32 v[32:33], v[0:1], v[0:1]
	v_cvt_pk_bf16_f32 v22, v0, v1
	v_pk_mul_f32 v[0:1], v[120:121], v[2:3] op_sel_hi:[0,1]
	v_pk_mul_f32 v[2:3], v[0:1], v[0:1]
	v_cvt_pk_bf16_f32 v21, v0, v1
	v_pk_mul_f32 v[0:1], v[120:121], v[4:5] op_sel_hi:[0,1]
	v_pk_mul_f32 v[4:5], v[120:121], v[6:7] op_sel_hi:[0,1]
	v_cvt_pk_bf16_f32 v20, v0, v1
	v_mov_b32_e32 v7, v0
	v_mov_b32_e32 v0, v5
	v_mov_b32_e32 v6, v4
	v_pk_mul_f32 v[0:1], v[0:1], v[0:1]
	v_cvt_pk_bf16_f32 v19, v4, v5
	v_pk_fma_f32 v[0:1], v[6:7], v[6:7], v[0:1]
	v_pk_mul_f32 v[4:5], v[120:121], v[8:9] op_sel_hi:[0,1]
	v_pk_mul_f32 v[6:7], v[120:121], v[10:11] op_sel_hi:[0,1]
	v_cvt_pk_bf16_f32 v18, v4, v5
	v_mov_b32_e32 v9, v4
	v_mov_b32_e32 v4, v7
	v_mov_b32_e32 v8, v6
	v_pk_mul_f32 v[4:5], v[4:5], v[4:5]
	v_cvt_pk_bf16_f32 v17, v6, v7
	v_pk_mul_f32 v[6:7], v[120:121], v[12:13] op_sel_hi:[0,1]
	v_pk_mul_f32 v[10:11], v[120:121], v[14:15] op_sel_hi:[0,1]
	v_pk_fma_f32 v[8:9], v[8:9], v[8:9], v[4:5]
	v_cvt_pk_bf16_f32 v5, v6, v7
	v_mov_b32_e32 v13, v6
	v_mov_b32_e32 v6, v11
	v_mov_b32_e32 v12, v10
	v_pk_mul_f32 v[6:7], v[6:7], v[6:7]
	v_add_f32_e32 v4, v124, v125
	v_pk_fma_f32 v[6:7], v[12:13], v[12:13], v[6:7]
	v_add_f32_e32 v12, v62, v63
	v_add_f32_e32 v13, v56, v57
	v_add_f32_e32 v12, v13, v12
	v_add_f32_e32 v4, v4, v12
	v_add_f32_e32 v12, v126, v127
	v_add_f32_e32 v4, v12, v4
	v_add_f32_e32 v12, v132, v133
	v_add_f32_e32 v4, v12, v4
	v_add_f32_e32 v12, v134, v135
	v_add_f32_e32 v4, v12, v4
	v_add_f32_e32 v12, v136, v137
	v_add_f32_e32 v4, v12, v4
	v_add_f32_e32 v12, v138, v139
	v_add_f32_e32 v4, v12, v4
	v_add_f32_e32 v12, v128, v129
	v_add_f32_e32 v4, v4, v12
	v_add_f32_e32 v12, v140, v141
	v_add_f32_e32 v4, v12, v4
	v_add_f32_e32 v12, v142, v143
	v_add_f32_e32 v4, v12, v4
	v_add_f32_e32 v12, v144, v145
	v_add_f32_e32 v4, v12, v4
	v_add_f32_e32 v12, v146, v147
	v_add_f32_e32 v4, v12, v4
	v_add_f32_e32 v12, v148, v149
	v_add_f32_e32 v4, v12, v4
	v_add_f32_e32 v12, v150, v151
	v_add_f32_e32 v4, v12, v4
	v_add_f32_e32 v12, v152, v153
	v_add_f32_e32 v4, v12, v4
	v_add_f32_e32 v12, v122, v123
	v_add_f32_e32 v4, v4, v12
	v_add_f32_e32 v12, v162, v163
	v_add_f32_e32 v4, v12, v4
	v_add_f32_e32 v12, v164, v165
	v_add_f32_e32 v4, v12, v4
	v_add_f32_e32 v12, v168, v169
	v_add_f32_e32 v4, v12, v4
	v_add_f32_e32 v12, v170, v171
	v_add_f32_e32 v4, v12, v4
	v_add_f32_e32 v12, v174, v175
	v_add_f32_e32 v4, v12, v4
	v_add_f32_e32 v12, v176, v177
	v_add_f32_e32 v4, v12, v4
	v_add_f32_e32 v12, v178, v179
	v_add_f32_e32 v4, v12, v4
	v_add_f32_e32 v12, v32, v33
	v_add_f32_e32 v4, v4, v12
	v_add_f32_e32 v2, v2, v3
	v_add_f32_e32 v2, v2, v4
	v_add_f32_e32 v1, v1, v2
	v_add_f32_e32 v0, v0, v1
	v_add_f32_e32 v0, v9, v0
	v_add_f32_e32 v0, v8, v0
	v_add_f32_e32 v0, v7, v0
	v_add_f32_e32 v0, v6, v0
	ds_bpermute_b32 v1, v159, v0
	v_cvt_pk_bf16_f32 v16, v10, v11
	v_lshlrev_b32_e32 v14, 16, v51
	s_waitcnt lgkmcnt(0)
	v_add_f32_e32 v0, v0, v1
	v_fmamk_f32 v0, v0, 0x3c000000, v231
	v_cmp_gt_f32_e32 vcc, s92, v0
	v_mul_f32_e32 v1, 0x4f800000, v0
	s_nop 0
	v_cndmask_b32_e32 v0, v0, v1, vcc
	v_sqrt_f32_e32 v1, v0
	s_nop 0
	v_add_u32_e32 v2, -1, v1
	v_fma_f32 v3, -v2, v1, v0
	v_cmp_ge_f32_e64 s[36:37], 0, v3
	v_add_u32_e32 v3, 1, v1
	s_nop 0
	v_cndmask_b32_e64 v2, v1, v2, s[36:37]
	v_fma_f32 v1, -v3, v1, v0
	v_cmp_lt_f32_e64 s[36:37], 0, v1
	s_nop 1
	v_cndmask_b32_e64 v1, v2, v3, s[36:37]
	v_mul_f32_e32 v2, 0x37800000, v1
	v_cndmask_b32_e32 v1, v1, v2, vcc
	v_cmp_class_f32_e32 vcc, v0, v232
	s_nop 1
	v_cndmask_b32_e32 v0, v1, v0, vcc
	v_div_scale_f32 v1, s[2:3], v0, v0, 1.0
	v_rcp_f32_e32 v2, v1
	s_nop 0
	v_fma_f32 v3, -v1, v2, 1.0
	v_fmac_f32_e32 v2, v3, v2
	v_div_scale_f32 v3, vcc, 1.0, v0, 1.0
	v_mul_f32_e32 v4, v3, v2
	v_fma_f32 v6, -v1, v4, v3
	v_fmac_f32_e32 v4, v6, v2
	v_fma_f32 v1, -v1, v4, v3
	v_div_fmas_f32 v1, v1, v2, v4
	v_div_fixup_f32 v4, v1, v0, 1.0
	flat_load_dwordx2 v[0:1], v[116:117] offset:136
	v_lshlrev_b64 v[2:3], 11, v[114:115]
	v_lshl_add_u64 v[6:7], s[64:65], 0, v[2:3]
	v_lshl_add_u64 v[6:7], v[6:7], 0, v[110:111]
	v_lshl_add_u64 v[2:3], s[60:61], 0, v[2:3]
	v_lshl_add_u64 v[2:3], v[2:3], 0, s[62:63]
	s_waitcnt vmcnt(0) lgkmcnt(0)
	v_lshl_add_u64 v[0:1], v[0:1], 0, s[44:45]
	v_lshl_add_u64 v[8:9], v[0:1], 0, v[112:113]
	global_load_dwordx2 v[0:1], v[6:7], off
	global_load_dwordx4 v[10:13], v[8:9], off
	s_waitcnt vmcnt(1)
	v_lshlrev_b32_e32 v15, 16, v0
	v_and_b32_e32 v0, 0xffff0000, v0
	v_mul_f32_e32 v0, 0xbfb8aa3b, v0
	v_exp_f32_e32 v0, v0
	v_mul_f32_e32 v15, 0xbfb8aa3b, v15
	v_exp_f32_e32 v15, v15
	v_add_f32_e32 v0, 1.0, v0
	v_rcp_f32_e32 v33, v0
	v_lshlrev_b32_e32 v0, 16, v1
	v_and_b32_e32 v1, 0xffff0000, v1
	v_mul_f32_e32 v0, 0xbfb8aa3b, v0
	v_mul_f32_e32 v1, 0xbfb8aa3b, v1
	v_exp_f32_e32 v0, v0
	v_exp_f32_e32 v1, v1
	v_add_f32_e32 v15, 1.0, v15
	v_rcp_f32_e32 v32, v15
	v_and_b32_e32 v15, 0xffff0000, v51
	v_add_f32_e32 v0, 1.0, v0
	v_add_f32_e32 v1, 1.0, v1
	v_pk_mul_f32 v[14:15], v[4:5], v[14:15] op_sel_hi:[0,1]
	v_rcp_f32_e32 v0, v0
	v_rcp_f32_e32 v1, v1
	s_waitcnt vmcnt(0)
	v_pk_mul_f32 v[10:11], v[10:11], v[14:15]
	v_lshlrev_b32_e32 v14, 16, v50
	v_and_b32_e32 v15, 0xffff0000, v50
	v_pk_mul_f32 v[14:15], v[4:5], v[14:15] op_sel_hi:[0,1]
	v_pk_mul_f32 v[12:13], v[12:13], v[14:15]
	v_pk_mul_f32 v[10:11], v[32:33], v[10:11]
	v_pk_mul_f32 v[12:13], v[0:1], v[12:13]
	v_cvt_pk_bf16_f32 v0, v10, v11
	v_cvt_pk_bf16_f32 v1, v12, v13
	v_lshl_add_u64 v[10:11], v[2:3], 0, v[110:111]
	global_store_dwordx2 v[10:11], v[0:1], off
	global_load_dwordx4 v[0:3], v[8:9], off offset:32
	s_nop 0
	global_load_dwordx2 v[12:13], v[6:7], off offset:16
	v_lshlrev_b32_e32 v14, 16, v49
	s_waitcnt vmcnt(0)
	v_lshlrev_b32_e32 v15, 16, v12
	v_and_b32_e32 v12, 0xffff0000, v12
	v_mul_f32_e32 v12, 0xbfb8aa3b, v12
	v_exp_f32_e32 v12, v12
	v_mul_f32_e32 v15, 0xbfb8aa3b, v15
	v_exp_f32_e32 v15, v15
	v_add_f32_e32 v12, 1.0, v12
	v_rcp_f32_e32 v33, v12
	v_lshlrev_b32_e32 v12, 16, v13
	v_and_b32_e32 v13, 0xffff0000, v13
	v_mul_f32_e32 v12, 0xbfb8aa3b, v12
	v_mul_f32_e32 v13, 0xbfb8aa3b, v13
	v_exp_f32_e32 v12, v12
	v_exp_f32_e32 v13, v13
	v_add_f32_e32 v15, 1.0, v15
	v_rcp_f32_e32 v32, v15
	v_and_b32_e32 v15, 0xffff0000, v49
	v_add_f32_e32 v12, 1.0, v12
	v_add_f32_e32 v13, 1.0, v13
	v_pk_mul_f32 v[14:15], v[4:5], v[14:15] op_sel_hi:[0,1]
	v_rcp_f32_e32 v12, v12
	v_rcp_f32_e32 v13, v13
	v_pk_mul_f32 v[0:1], v[0:1], v[14:15]
	v_lshlrev_b32_e32 v14, 16, v48
	v_and_b32_e32 v15, 0xffff0000, v48
	v_pk_mul_f32 v[14:15], v[4:5], v[14:15] op_sel_hi:[0,1]
	v_pk_mul_f32 v[2:3], v[2:3], v[14:15]
	v_pk_mul_f32 v[0:1], v[32:33], v[0:1]
	v_pk_mul_f32 v[2:3], v[12:13], v[2:3]
	v_cvt_pk_bf16_f32 v0, v0, v1
	v_cvt_pk_bf16_f32 v1, v2, v3
	global_store_dwordx2 v[10:11], v[0:1], off offset:16
	global_load_dwordx4 v[0:3], v[8:9], off offset:64
	s_nop 0
	global_load_dwordx2 v[12:13], v[6:7], off offset:32
	v_lshlrev_b32_e32 v14, 16, v47
	s_waitcnt vmcnt(0)
	v_lshlrev_b32_e32 v15, 16, v12
	v_and_b32_e32 v12, 0xffff0000, v12
	v_mul_f32_e32 v12, 0xbfb8aa3b, v12
	v_exp_f32_e32 v12, v12
	v_mul_f32_e32 v15, 0xbfb8aa3b, v15
	v_exp_f32_e32 v15, v15
	v_add_f32_e32 v12, 1.0, v12
	v_rcp_f32_e32 v33, v12
	v_lshlrev_b32_e32 v12, 16, v13
	v_and_b32_e32 v13, 0xffff0000, v13
	v_mul_f32_e32 v12, 0xbfb8aa3b, v12
	v_mul_f32_e32 v13, 0xbfb8aa3b, v13
	v_exp_f32_e32 v12, v12
	v_exp_f32_e32 v13, v13
	v_add_f32_e32 v15, 1.0, v15
	v_rcp_f32_e32 v32, v15
	v_and_b32_e32 v15, 0xffff0000, v47
	v_add_f32_e32 v12, 1.0, v12
	v_add_f32_e32 v13, 1.0, v13
	v_pk_mul_f32 v[14:15], v[4:5], v[14:15] op_sel_hi:[0,1]
	v_rcp_f32_e32 v12, v12
	v_rcp_f32_e32 v13, v13
	v_pk_mul_f32 v[0:1], v[0:1], v[14:15]
	v_lshlrev_b32_e32 v14, 16, v46
	v_and_b32_e32 v15, 0xffff0000, v46
	v_pk_mul_f32 v[14:15], v[4:5], v[14:15] op_sel_hi:[0,1]
	v_pk_mul_f32 v[2:3], v[2:3], v[14:15]
	v_pk_mul_f32 v[0:1], v[32:33], v[0:1]
	v_pk_mul_f32 v[2:3], v[12:13], v[2:3]
	v_cvt_pk_bf16_f32 v0, v0, v1
	v_cvt_pk_bf16_f32 v1, v2, v3
	global_store_dwordx2 v[10:11], v[0:1], off offset:32
	global_load_dwordx4 v[0:3], v[8:9], off offset:96
	s_nop 0
	global_load_dwordx2 v[12:13], v[6:7], off offset:48
	v_lshlrev_b32_e32 v14, 16, v45
	s_waitcnt vmcnt(0)
	v_lshlrev_b32_e32 v15, 16, v12
	v_and_b32_e32 v12, 0xffff0000, v12
	v_mul_f32_e32 v12, 0xbfb8aa3b, v12
	v_exp_f32_e32 v12, v12
	v_mul_f32_e32 v15, 0xbfb8aa3b, v15
	v_exp_f32_e32 v15, v15
	v_add_f32_e32 v12, 1.0, v12
	v_rcp_f32_e32 v33, v12
	v_lshlrev_b32_e32 v12, 16, v13
	v_and_b32_e32 v13, 0xffff0000, v13
	v_mul_f32_e32 v12, 0xbfb8aa3b, v12
	v_mul_f32_e32 v13, 0xbfb8aa3b, v13
	v_exp_f32_e32 v12, v12
	v_exp_f32_e32 v13, v13
	v_add_f32_e32 v15, 1.0, v15
	v_rcp_f32_e32 v32, v15
	v_and_b32_e32 v15, 0xffff0000, v45
	v_add_f32_e32 v12, 1.0, v12
	v_add_f32_e32 v13, 1.0, v13
	v_pk_mul_f32 v[14:15], v[4:5], v[14:15] op_sel_hi:[0,1]
	v_rcp_f32_e32 v12, v12
	v_rcp_f32_e32 v13, v13
	v_pk_mul_f32 v[0:1], v[0:1], v[14:15]
	v_lshlrev_b32_e32 v14, 16, v44
	v_and_b32_e32 v15, 0xffff0000, v44
	v_pk_mul_f32 v[14:15], v[4:5], v[14:15] op_sel_hi:[0,1]
	v_pk_mul_f32 v[2:3], v[2:3], v[14:15]
	v_pk_mul_f32 v[0:1], v[0:1], v[32:33]
	v_pk_mul_f32 v[2:3], v[2:3], v[12:13]
	v_cvt_pk_bf16_f32 v0, v0, v1
	v_cvt_pk_bf16_f32 v1, v2, v3
	global_store_dwordx2 v[10:11], v[0:1], off offset:48
	global_load_dwordx4 v[0:3], v[8:9], off offset:128
	s_nop 0
	global_load_dwordx2 v[12:13], v[6:7], off offset:64
	v_lshlrev_b32_e32 v14, 16, v43
	s_waitcnt vmcnt(0)
	v_lshlrev_b32_e32 v15, 16, v12
	v_and_b32_e32 v12, 0xffff0000, v12
	v_mul_f32_e32 v12, 0xbfb8aa3b, v12
	v_exp_f32_e32 v12, v12
	v_mul_f32_e32 v15, 0xbfb8aa3b, v15
	v_exp_f32_e32 v15, v15
	v_add_f32_e32 v12, 1.0, v12
	v_rcp_f32_e32 v33, v12
	v_lshlrev_b32_e32 v12, 16, v13
	v_and_b32_e32 v13, 0xffff0000, v13
	v_mul_f32_e32 v12, 0xbfb8aa3b, v12
	v_mul_f32_e32 v13, 0xbfb8aa3b, v13
	v_exp_f32_e32 v12, v12
	v_exp_f32_e32 v13, v13
	v_add_f32_e32 v15, 1.0, v15
	v_rcp_f32_e32 v32, v15
	v_and_b32_e32 v15, 0xffff0000, v43
	v_add_f32_e32 v12, 1.0, v12
	v_add_f32_e32 v13, 1.0, v13
	v_pk_mul_f32 v[14:15], v[4:5], v[14:15] op_sel_hi:[0,1]
	v_rcp_f32_e32 v12, v12
	v_rcp_f32_e32 v13, v13
	v_pk_mul_f32 v[0:1], v[0:1], v[14:15]
	v_lshlrev_b32_e32 v14, 16, v42
	v_and_b32_e32 v15, 0xffff0000, v42
	v_pk_mul_f32 v[14:15], v[4:5], v[14:15] op_sel_hi:[0,1]
	v_pk_mul_f32 v[2:3], v[2:3], v[14:15]
	v_pk_mul_f32 v[0:1], v[0:1], v[32:33]
	v_pk_mul_f32 v[2:3], v[2:3], v[12:13]
	v_cvt_pk_bf16_f32 v0, v0, v1
	v_cvt_pk_bf16_f32 v1, v2, v3
	global_store_dwordx2 v[10:11], v[0:1], off offset:64
	global_load_dwordx4 v[0:3], v[8:9], off offset:160
	s_nop 0
	global_load_dwordx2 v[12:13], v[6:7], off offset:80
	v_lshlrev_b32_e32 v14, 16, v41
	s_waitcnt vmcnt(0)
	v_lshlrev_b32_e32 v15, 16, v12
	v_and_b32_e32 v12, 0xffff0000, v12
	v_mul_f32_e32 v12, 0xbfb8aa3b, v12
	v_exp_f32_e32 v12, v12
	v_mul_f32_e32 v15, 0xbfb8aa3b, v15
	v_exp_f32_e32 v15, v15
	v_add_f32_e32 v12, 1.0, v12
	v_rcp_f32_e32 v33, v12
	v_lshlrev_b32_e32 v12, 16, v13
	v_and_b32_e32 v13, 0xffff0000, v13
	v_mul_f32_e32 v12, 0xbfb8aa3b, v12
	v_mul_f32_e32 v13, 0xbfb8aa3b, v13
	v_exp_f32_e32 v12, v12
	v_exp_f32_e32 v13, v13
	v_add_f32_e32 v15, 1.0, v15
	v_rcp_f32_e32 v32, v15
	v_and_b32_e32 v15, 0xffff0000, v41
	v_add_f32_e32 v12, 1.0, v12
	v_add_f32_e32 v13, 1.0, v13
	v_pk_mul_f32 v[14:15], v[4:5], v[14:15] op_sel_hi:[0,1]
	v_rcp_f32_e32 v12, v12
	v_rcp_f32_e32 v13, v13
	v_pk_mul_f32 v[0:1], v[14:15], v[0:1]
	v_lshlrev_b32_e32 v14, 16, v40
	v_and_b32_e32 v15, 0xffff0000, v40
	v_pk_mul_f32 v[14:15], v[4:5], v[14:15] op_sel_hi:[0,1]
	v_pk_mul_f32 v[2:3], v[14:15], v[2:3]
	v_pk_mul_f32 v[0:1], v[0:1], v[32:33]
	v_pk_mul_f32 v[2:3], v[2:3], v[12:13]
	v_cvt_pk_bf16_f32 v0, v0, v1
	v_cvt_pk_bf16_f32 v1, v2, v3
	global_store_dwordx2 v[10:11], v[0:1], off offset:80
	global_load_dwordx4 v[0:3], v[8:9], off offset:192
	s_nop 0
	global_load_dwordx2 v[12:13], v[6:7], off offset:96
	v_lshlrev_b32_e32 v14, 16, v39
	s_waitcnt vmcnt(0)
	v_lshlrev_b32_e32 v15, 16, v12
	v_and_b32_e32 v12, 0xffff0000, v12
	v_mul_f32_e32 v12, 0xbfb8aa3b, v12
	v_exp_f32_e32 v12, v12
	v_mul_f32_e32 v15, 0xbfb8aa3b, v15
	v_exp_f32_e32 v15, v15
	v_add_f32_e32 v12, 1.0, v12
	v_rcp_f32_e32 v33, v12
	v_lshlrev_b32_e32 v12, 16, v13
	v_and_b32_e32 v13, 0xffff0000, v13
	v_mul_f32_e32 v12, 0xbfb8aa3b, v12
	v_mul_f32_e32 v13, 0xbfb8aa3b, v13
	v_exp_f32_e32 v12, v12
	v_exp_f32_e32 v13, v13
	v_add_f32_e32 v15, 1.0, v15
	v_rcp_f32_e32 v32, v15
	v_and_b32_e32 v15, 0xffff0000, v39
	v_add_f32_e32 v12, 1.0, v12
	v_add_f32_e32 v13, 1.0, v13
	v_pk_mul_f32 v[14:15], v[4:5], v[14:15] op_sel_hi:[0,1]
	v_rcp_f32_e32 v12, v12
	v_rcp_f32_e32 v13, v13
	v_pk_mul_f32 v[0:1], v[14:15], v[0:1]
	v_lshlrev_b32_e32 v14, 16, v38
	v_and_b32_e32 v15, 0xffff0000, v38
	v_pk_mul_f32 v[14:15], v[4:5], v[14:15] op_sel_hi:[0,1]
	v_pk_mul_f32 v[2:3], v[14:15], v[2:3]
	v_pk_mul_f32 v[0:1], v[0:1], v[32:33]
	v_pk_mul_f32 v[2:3], v[2:3], v[12:13]
	v_cvt_pk_bf16_f32 v0, v0, v1
	v_cvt_pk_bf16_f32 v1, v2, v3
	global_store_dwordx2 v[10:11], v[0:1], off offset:96
	global_load_dwordx4 v[0:3], v[8:9], off offset:224
	s_nop 0
	global_load_dwordx2 v[12:13], v[6:7], off offset:112
	v_lshlrev_b32_e32 v14, 16, v37
	s_waitcnt vmcnt(0)
	v_lshlrev_b32_e32 v15, 16, v12
	v_and_b32_e32 v12, 0xffff0000, v12
	v_mul_f32_e32 v12, 0xbfb8aa3b, v12
	v_exp_f32_e32 v12, v12
	v_mul_f32_e32 v15, 0xbfb8aa3b, v15
	v_exp_f32_e32 v15, v15
	v_add_f32_e32 v12, 1.0, v12
	v_rcp_f32_e32 v33, v12
	v_lshlrev_b32_e32 v12, 16, v13
	v_and_b32_e32 v13, 0xffff0000, v13
	v_mul_f32_e32 v12, 0xbfb8aa3b, v12
	v_mul_f32_e32 v13, 0xbfb8aa3b, v13
	v_exp_f32_e32 v12, v12
	v_exp_f32_e32 v13, v13
	v_add_f32_e32 v15, 1.0, v15
	v_rcp_f32_e32 v32, v15
	v_and_b32_e32 v15, 0xffff0000, v37
	v_add_f32_e32 v12, 1.0, v12
	v_add_f32_e32 v13, 1.0, v13
	v_pk_mul_f32 v[14:15], v[4:5], v[14:15] op_sel_hi:[0,1]
	v_rcp_f32_e32 v12, v12
	v_rcp_f32_e32 v13, v13
	v_pk_mul_f32 v[0:1], v[14:15], v[0:1]
	v_lshlrev_b32_e32 v14, 16, v36
	v_and_b32_e32 v15, 0xffff0000, v36
	v_pk_mul_f32 v[14:15], v[4:5], v[14:15] op_sel_hi:[0,1]
	v_pk_mul_f32 v[2:3], v[14:15], v[2:3]
	v_pk_mul_f32 v[0:1], v[0:1], v[32:33]
	v_pk_mul_f32 v[2:3], v[2:3], v[12:13]
	v_cvt_pk_bf16_f32 v0, v0, v1
	v_cvt_pk_bf16_f32 v1, v2, v3
	global_store_dwordx2 v[10:11], v[0:1], off offset:112
	global_load_dwordx4 v[0:3], v[8:9], off offset:256
	s_nop 0
	global_load_dwordx2 v[12:13], v[6:7], off offset:128
	v_lshlrev_b32_e32 v14, 16, v31
	s_waitcnt vmcnt(0)
	v_lshlrev_b32_e32 v15, 16, v12
	v_and_b32_e32 v12, 0xffff0000, v12
	v_mul_f32_e32 v12, 0xbfb8aa3b, v12
	v_exp_f32_e32 v12, v12
	v_mul_f32_e32 v15, 0xbfb8aa3b, v15
	v_exp_f32_e32 v15, v15
	v_add_f32_e32 v12, 1.0, v12
	v_rcp_f32_e32 v33, v12
	v_lshlrev_b32_e32 v12, 16, v13
	v_and_b32_e32 v13, 0xffff0000, v13
	v_mul_f32_e32 v12, 0xbfb8aa3b, v12
	v_mul_f32_e32 v13, 0xbfb8aa3b, v13
	v_exp_f32_e32 v12, v12
	v_exp_f32_e32 v13, v13
	v_add_f32_e32 v15, 1.0, v15
	v_rcp_f32_e32 v32, v15
	v_and_b32_e32 v15, 0xffff0000, v31
	v_add_f32_e32 v12, 1.0, v12
	v_add_f32_e32 v13, 1.0, v13
	v_pk_mul_f32 v[14:15], v[4:5], v[14:15] op_sel_hi:[0,1]
	v_rcp_f32_e32 v12, v12
	v_rcp_f32_e32 v13, v13
	v_pk_mul_f32 v[0:1], v[14:15], v[0:1]
	v_lshlrev_b32_e32 v14, 16, v30
	v_and_b32_e32 v15, 0xffff0000, v30
	v_pk_mul_f32 v[14:15], v[4:5], v[14:15] op_sel_hi:[0,1]
	v_pk_mul_f32 v[2:3], v[14:15], v[2:3]
	v_pk_mul_f32 v[0:1], v[0:1], v[32:33]
	v_pk_mul_f32 v[2:3], v[2:3], v[12:13]
	v_cvt_pk_bf16_f32 v0, v0, v1
	v_cvt_pk_bf16_f32 v1, v2, v3
	global_store_dwordx2 v[10:11], v[0:1], off offset:128
	global_load_dwordx4 v[0:3], v[8:9], off offset:288
	s_nop 0
	global_load_dwordx2 v[12:13], v[6:7], off offset:144
	v_lshlrev_b32_e32 v14, 16, v29
	s_waitcnt vmcnt(0)
	v_lshlrev_b32_e32 v15, 16, v12
	v_and_b32_e32 v12, 0xffff0000, v12
	v_mul_f32_e32 v12, 0xbfb8aa3b, v12
	v_exp_f32_e32 v12, v12
	v_mul_f32_e32 v15, 0xbfb8aa3b, v15
	v_exp_f32_e32 v15, v15
	v_add_f32_e32 v12, 1.0, v12
	v_rcp_f32_e32 v31, v12
	v_lshlrev_b32_e32 v12, 16, v13
	v_and_b32_e32 v13, 0xffff0000, v13
	v_mul_f32_e32 v12, 0xbfb8aa3b, v12
	v_mul_f32_e32 v13, 0xbfb8aa3b, v13
	v_exp_f32_e32 v12, v12
	v_exp_f32_e32 v13, v13
	v_add_f32_e32 v15, 1.0, v15
	v_rcp_f32_e32 v30, v15
	v_and_b32_e32 v15, 0xffff0000, v29
	v_add_f32_e32 v12, 1.0, v12
	v_add_f32_e32 v13, 1.0, v13
	v_pk_mul_f32 v[14:15], v[4:5], v[14:15] op_sel_hi:[0,1]
	v_rcp_f32_e32 v12, v12
	v_rcp_f32_e32 v13, v13
	v_pk_mul_f32 v[0:1], v[14:15], v[0:1]
	v_lshlrev_b32_e32 v14, 16, v28
	v_and_b32_e32 v15, 0xffff0000, v28
	v_pk_mul_f32 v[14:15], v[4:5], v[14:15] op_sel_hi:[0,1]
	v_pk_mul_f32 v[2:3], v[14:15], v[2:3]
	v_pk_mul_f32 v[0:1], v[0:1], v[30:31]
	v_pk_mul_f32 v[2:3], v[2:3], v[12:13]
	v_cvt_pk_bf16_f32 v0, v0, v1
	v_cvt_pk_bf16_f32 v1, v2, v3
	global_store_dwordx2 v[10:11], v[0:1], off offset:144
	global_load_dwordx4 v[0:3], v[8:9], off offset:320
	s_nop 0
	global_load_dwordx2 v[12:13], v[6:7], off offset:160
	v_lshlrev_b32_e32 v14, 16, v27
	s_waitcnt vmcnt(0)
	v_lshlrev_b32_e32 v15, 16, v12
	v_and_b32_e32 v12, 0xffff0000, v12
	v_mul_f32_e32 v12, 0xbfb8aa3b, v12
	v_exp_f32_e32 v12, v12
	v_mul_f32_e32 v15, 0xbfb8aa3b, v15
	v_exp_f32_e32 v15, v15
	v_add_f32_e32 v12, 1.0, v12
	v_rcp_f32_e32 v29, v12
	v_lshlrev_b32_e32 v12, 16, v13
	v_and_b32_e32 v13, 0xffff0000, v13
	v_mul_f32_e32 v12, 0xbfb8aa3b, v12
	v_mul_f32_e32 v13, 0xbfb8aa3b, v13
	v_exp_f32_e32 v12, v12
	v_exp_f32_e32 v13, v13
	v_add_f32_e32 v15, 1.0, v15
	v_rcp_f32_e32 v28, v15
	v_and_b32_e32 v15, 0xffff0000, v27
	v_add_f32_e32 v12, 1.0, v12
	v_add_f32_e32 v13, 1.0, v13
	v_pk_mul_f32 v[14:15], v[4:5], v[14:15] op_sel_hi:[0,1]
	v_rcp_f32_e32 v12, v12
	v_rcp_f32_e32 v13, v13
	v_pk_mul_f32 v[0:1], v[14:15], v[0:1]
	v_lshlrev_b32_e32 v14, 16, v26
	v_and_b32_e32 v15, 0xffff0000, v26
	v_pk_mul_f32 v[14:15], v[4:5], v[14:15] op_sel_hi:[0,1]
	v_pk_mul_f32 v[2:3], v[14:15], v[2:3]
	v_pk_mul_f32 v[0:1], v[0:1], v[28:29]
	v_pk_mul_f32 v[2:3], v[2:3], v[12:13]
	v_cvt_pk_bf16_f32 v0, v0, v1
	v_cvt_pk_bf16_f32 v1, v2, v3
	global_store_dwordx2 v[10:11], v[0:1], off offset:160
	global_load_dwordx4 v[0:3], v[8:9], off offset:352
	s_nop 0
	global_load_dwordx2 v[12:13], v[6:7], off offset:176
	v_lshlrev_b32_e32 v14, 16, v25
	s_waitcnt vmcnt(0)
	v_lshlrev_b32_e32 v15, 16, v12
	v_and_b32_e32 v12, 0xffff0000, v12
	v_mul_f32_e32 v12, 0xbfb8aa3b, v12
	v_exp_f32_e32 v12, v12
	v_mul_f32_e32 v15, 0xbfb8aa3b, v15
	v_exp_f32_e32 v15, v15
	v_add_f32_e32 v12, 1.0, v12
	v_rcp_f32_e32 v27, v12
	v_lshlrev_b32_e32 v12, 16, v13
	v_and_b32_e32 v13, 0xffff0000, v13
	v_mul_f32_e32 v12, 0xbfb8aa3b, v12
	v_mul_f32_e32 v13, 0xbfb8aa3b, v13
	v_exp_f32_e32 v12, v12
	v_exp_f32_e32 v13, v13
	v_add_f32_e32 v15, 1.0, v15
	v_rcp_f32_e32 v26, v15
	v_and_b32_e32 v15, 0xffff0000, v25
	v_add_f32_e32 v12, 1.0, v12
	v_add_f32_e32 v13, 1.0, v13
	v_pk_mul_f32 v[14:15], v[4:5], v[14:15] op_sel_hi:[0,1]
	v_rcp_f32_e32 v12, v12
	v_rcp_f32_e32 v13, v13
	v_pk_mul_f32 v[0:1], v[14:15], v[0:1]
	v_lshlrev_b32_e32 v14, 16, v24
	v_and_b32_e32 v15, 0xffff0000, v24
	v_pk_mul_f32 v[14:15], v[4:5], v[14:15] op_sel_hi:[0,1]
	v_pk_mul_f32 v[2:3], v[14:15], v[2:3]
	v_pk_mul_f32 v[0:1], v[0:1], v[26:27]
	v_pk_mul_f32 v[2:3], v[2:3], v[12:13]
	v_cvt_pk_bf16_f32 v0, v0, v1
	v_cvt_pk_bf16_f32 v1, v2, v3
	global_store_dwordx2 v[10:11], v[0:1], off offset:176
	global_load_dwordx4 v[0:3], v[8:9], off offset:384
	s_nop 0
	global_load_dwordx2 v[12:13], v[6:7], off offset:192
	v_lshlrev_b32_e32 v14, 16, v22
	s_waitcnt vmcnt(0)
	v_lshlrev_b32_e32 v15, 16, v12
	v_and_b32_e32 v12, 0xffff0000, v12
	v_mul_f32_e32 v12, 0xbfb8aa3b, v12
	v_exp_f32_e32 v12, v12
	v_mul_f32_e32 v15, 0xbfb8aa3b, v15
	v_exp_f32_e32 v15, v15
	v_add_f32_e32 v12, 1.0, v12
	v_rcp_f32_e32 v25, v12
	v_lshlrev_b32_e32 v12, 16, v13
	v_and_b32_e32 v13, 0xffff0000, v13
	v_mul_f32_e32 v12, 0xbfb8aa3b, v12
	v_mul_f32_e32 v13, 0xbfb8aa3b, v13
	v_exp_f32_e32 v12, v12
	v_exp_f32_e32 v13, v13
	v_add_f32_e32 v15, 1.0, v15
	v_rcp_f32_e32 v24, v15
	v_and_b32_e32 v15, 0xffff0000, v22
	v_add_f32_e32 v12, 1.0, v12
	v_add_f32_e32 v13, 1.0, v13
	v_pk_mul_f32 v[14:15], v[4:5], v[14:15] op_sel_hi:[0,1]
	v_rcp_f32_e32 v12, v12
	v_rcp_f32_e32 v13, v13
	v_pk_mul_f32 v[0:1], v[14:15], v[0:1]
	v_lshlrev_b32_e32 v14, 16, v21
	v_and_b32_e32 v15, 0xffff0000, v21
	v_pk_mul_f32 v[14:15], v[4:5], v[14:15] op_sel_hi:[0,1]
	v_pk_mul_f32 v[2:3], v[14:15], v[2:3]
	v_pk_mul_f32 v[0:1], v[0:1], v[24:25]
	v_pk_mul_f32 v[2:3], v[2:3], v[12:13]
	v_cvt_pk_bf16_f32 v0, v0, v1
	v_cvt_pk_bf16_f32 v1, v2, v3
	global_store_dwordx2 v[10:11], v[0:1], off offset:192
	global_load_dwordx4 v[0:3], v[8:9], off offset:416
	s_nop 0
	global_load_dwordx2 v[12:13], v[6:7], off offset:208
	v_lshlrev_b32_e32 v14, 16, v20
	s_waitcnt vmcnt(0)
	v_lshlrev_b32_e32 v15, 16, v12
	v_and_b32_e32 v12, 0xffff0000, v12
	v_mul_f32_e32 v12, 0xbfb8aa3b, v12
	v_exp_f32_e32 v12, v12
	v_mul_f32_e32 v15, 0xbfb8aa3b, v15
	v_exp_f32_e32 v15, v15
	v_add_f32_e32 v12, 1.0, v12
	v_rcp_f32_e32 v23, v12
	v_lshlrev_b32_e32 v12, 16, v13
	v_and_b32_e32 v13, 0xffff0000, v13
	v_mul_f32_e32 v12, 0xbfb8aa3b, v12
	v_mul_f32_e32 v13, 0xbfb8aa3b, v13
	v_exp_f32_e32 v12, v12
	v_exp_f32_e32 v13, v13
	v_add_f32_e32 v15, 1.0, v15
	v_rcp_f32_e32 v22, v15
	v_and_b32_e32 v15, 0xffff0000, v20
	v_add_f32_e32 v12, 1.0, v12
	v_add_f32_e32 v13, 1.0, v13
	v_pk_mul_f32 v[14:15], v[4:5], v[14:15] op_sel_hi:[0,1]
	v_rcp_f32_e32 v12, v12
	v_rcp_f32_e32 v13, v13
	v_pk_mul_f32 v[0:1], v[14:15], v[0:1]
	v_lshlrev_b32_e32 v14, 16, v19
	v_and_b32_e32 v15, 0xffff0000, v19
	v_pk_mul_f32 v[14:15], v[4:5], v[14:15] op_sel_hi:[0,1]
	v_pk_mul_f32 v[2:3], v[14:15], v[2:3]
	v_pk_mul_f32 v[0:1], v[0:1], v[22:23]
	v_pk_mul_f32 v[2:3], v[2:3], v[12:13]
	v_cvt_pk_bf16_f32 v0, v0, v1
	v_cvt_pk_bf16_f32 v1, v2, v3
	global_store_dwordx2 v[10:11], v[0:1], off offset:208
	global_load_dwordx4 v[0:3], v[8:9], off offset:448
	s_nop 0
	global_load_dwordx2 v[12:13], v[6:7], off offset:224
	v_lshlrev_b32_e32 v14, 16, v18
	s_waitcnt vmcnt(0)
	v_lshlrev_b32_e32 v15, 16, v12
	v_and_b32_e32 v12, 0xffff0000, v12
	v_mul_f32_e32 v12, 0xbfb8aa3b, v12
	v_exp_f32_e32 v12, v12
	v_mul_f32_e32 v15, 0xbfb8aa3b, v15
	v_exp_f32_e32 v15, v15
	v_add_f32_e32 v12, 1.0, v12
	v_rcp_f32_e32 v21, v12
	v_lshlrev_b32_e32 v12, 16, v13
	v_and_b32_e32 v13, 0xffff0000, v13
	v_mul_f32_e32 v12, 0xbfb8aa3b, v12
	v_mul_f32_e32 v13, 0xbfb8aa3b, v13
	v_exp_f32_e32 v12, v12
	v_exp_f32_e32 v13, v13
	v_add_f32_e32 v15, 1.0, v15
	v_rcp_f32_e32 v20, v15
	v_and_b32_e32 v15, 0xffff0000, v18
	v_add_f32_e32 v12, 1.0, v12
	v_add_f32_e32 v13, 1.0, v13
	v_pk_mul_f32 v[14:15], v[4:5], v[14:15] op_sel_hi:[0,1]
	v_rcp_f32_e32 v12, v12
	v_rcp_f32_e32 v13, v13
	v_pk_mul_f32 v[0:1], v[14:15], v[0:1]
	v_lshlrev_b32_e32 v14, 16, v17
	v_and_b32_e32 v15, 0xffff0000, v17
	v_pk_mul_f32 v[14:15], v[4:5], v[14:15] op_sel_hi:[0,1]
	v_pk_mul_f32 v[2:3], v[14:15], v[2:3]
	v_pk_mul_f32 v[0:1], v[0:1], v[20:21]
	v_pk_mul_f32 v[2:3], v[2:3], v[12:13]
	v_cvt_pk_bf16_f32 v0, v0, v1
	v_cvt_pk_bf16_f32 v1, v2, v3
	global_store_dwordx2 v[10:11], v[0:1], off offset:224
	global_load_dwordx4 v[0:3], v[8:9], off offset:480
	s_nop 0
	global_load_dwordx2 v[6:7], v[6:7], off offset:240
	v_lshlrev_b32_e32 v8, 16, v5
	s_waitcnt vmcnt(0)
	v_lshlrev_b32_e32 v9, 16, v6
	v_mul_f32_e32 v9, 0xbfb8aa3b, v9
	v_exp_f32_e32 v9, v9
	s_nop 0
	v_add_f32_e32 v9, 1.0, v9
	v_rcp_f32_e32 v12, v9
	v_and_b32_e32 v9, 0xffff0000, v5
	v_and_b32_e32 v5, 0xffff0000, v6
	v_mul_f32_e32 v5, 0xbfb8aa3b, v5
	v_exp_f32_e32 v5, v5
	s_nop 0
	v_add_f32_e32 v5, 1.0, v5
	v_rcp_f32_e32 v13, v5
	v_pk_mul_f32 v[8:9], v[4:5], v[8:9] op_sel_hi:[0,1]
	v_lshlrev_b32_e32 v5, 16, v7
	v_mul_f32_e32 v5, 0xbfb8aa3b, v5
	v_exp_f32_e32 v5, v5
	v_pk_mul_f32 v[0:1], v[8:9], v[0:1]
	v_lshlrev_b32_e32 v8, 16, v16
	v_and_b32_e32 v9, 0xffff0000, v16
	v_add_f32_e32 v5, 1.0, v5
	v_rcp_f32_e32 v6, v5
	v_and_b32_e32 v5, 0xffff0000, v7
	v_mul_f32_e32 v5, 0xbfb8aa3b, v5
	v_exp_f32_e32 v5, v5
	v_pk_mul_f32 v[0:1], v[0:1], v[12:13]
	v_add_f32_e32 v5, 1.0, v5
	v_rcp_f32_e32 v7, v5
	v_pk_mul_f32 v[4:5], v[4:5], v[8:9] op_sel_hi:[0,1]
	v_pk_mul_f32 v[2:3], v[4:5], v[2:3]
	v_cvt_pk_bf16_f32 v0, v0, v1
	v_pk_mul_f32 v[2:3], v[2:3], v[6:7]
	s_nop 0
	v_cvt_pk_bf16_f32 v1, v2, v3
	global_store_dwordx2 v[10:11], v[0:1], off offset:240
	s_waitcnt lgkmcnt(0)
	s_cbranch_scc1 .LBB0_1656
	v_readlane_b32 s78, v254, 19
	v_readlane_b32 s79, v254, 20
	v_readlane_b32 s72, v255, 46
	s_brev_b32 s84, 63
	v_readlane_b32 s73, v255, 47
	v_readlane_b32 s66, v255, 48
	v_readlane_b32 s68, v255, 50
	s_movk_i32 s69, 0x2000
	s_movk_i32 s79, 0x4080
	s_mov_b32 s70, 0xf800000
	s_mov_b32 s85, -1
	v_readlane_b32 s74, v255, 51
	v_readlane_b32 s67, v255, 49
